# RG-LRU gates: the MFMAs of the next 32-row gate group are woven into the VALU stream of the current one (second accumulator set)
# speedup vs baseline: 1.0063x; 1.0011x over previous
; #define LAS __attribute__((address_space(3)))
; __device__ __forceinline__ unsigned pk2(float lo, float hi) { f32x2_t v = {lo, hi}; bf16x2_t b = __builtin_convertvector(v, bf16x2_t); return __builtin_bit_cast(unsigned, b); }
; __device__ __forceinline__ float bflo(unsigned u) { return __uint_as_float(u << 16); }
; __device__ __forceinline__ float bfhi(unsigned u) { return __uint_as_float(u & 0xffff0000u); }
; __device__ __forceinline__ void lru_phase(const Ptrs& P, LAS unsigned char* lds, int G, int wave, int lane, int tid) {
;     ...
;           for (int s = 0; s < 5; ++s) { unsigned pkd[4];
; #pragma unroll
;               for (int half = 0; half < 2; ++half) { const int ch0 = 16 * s + 8 * half;
;                   const f32x4 cb = *(const LAS f32x4*)(par + 4 * LB + ch0 + 4 * hh);
;                   float a0 = cb[0], a1 = cb[1], a2 = cb[2], a3 = cb[3];
; #pragma unroll
;                   for (int tap = 0; tap < 4; ++tap) { const v2u rw = raw[s * 2 + half][tap];
;                       const f32x4 cw = *(const LAS f32x4*)(par + tap * LB + ch0 + 4 * hh);
;                       float c0 = cw[0], c1 = cw[1], c2 = cw[2], c3 = cw[3]; asm("" : "+v"(c0), "+v"(c1), "+v"(c2), "+v"(c3));
;                       a0 = __builtin_fmaf(c0, bflo(rw.x), a0); a1 = __builtin_fmaf(c1, bfhi(rw.x), a1); a2 = __builtin_fmaf(c2, bflo(rw.y), a2); a3 = __builtin_fmaf(c3, bfhi(rw.y), a3); }
;                   asm volatile("" : "+v"(a0), "+v"(a1), "+v"(a2), "+v"(a3));
;                   xc[s][half][0] = a0; xc[s][half][1] = a1; xc[s][half][2] = a2; xc[s][half][3] = a3;
;                   pkd[2 * half] = pk2(a0, a1); pkd[2 * half + 1] = pk2(a2, a3); __builtin_amdgcn_sched_barrier(0); }
;               v4u t = {pkd[0], pkd[1], pkd[2], pkd[3]}; xf[s] = __builtin_bit_cast(bf16x8, t); __builtin_amdgcn_sched_barrier(0); } }
.LBB0_308:
	s_ashr_i32 s35, s20, 6
	s_lshl_b32 s34, s35, 8
	s_bfe_u32 s31, s20, 0x20004
	s_add_i32 s34, s34, s26
	ds_read_b128 v[0:3], v234 offset:36864
	ds_read_b128 v[48:51], v234 offset:38144
	ds_read_b128 v[4:7], v234 offset:37184
	s_waitcnt vmcnt(33)
	v_lshlrev_b32_e32 v8, 16, v36
	s_waitcnt lgkmcnt(2)
	s_waitcnt lgkmcnt(1)
	v_fma_f32 v45, v0, v8, v48
	v_and_b32_e32 v0, 0xffff0000, v36
	v_fma_f32 v46, v1, v0, v49
	v_lshlrev_b32_e32 v0, 16, v37
	v_fma_f32 v50, v2, v0, v50
	v_and_b32_e32 v0, 0xffff0000, v37
	v_fmac_f32_e32 v51, v3, v0
	s_waitcnt lgkmcnt(0)
	v_mov_b32_e32 v0, v5
	v_mov_b32_e32 v5, v7
	v_mov_b32_e32 v1, v4
	s_waitcnt vmcnt(23)
	v_lshlrev_b32_e32 v2, 16, v168
	v_lshlrev_b32_e32 v4, 16, v169
	v_fmac_f32_e32 v45, v1, v2
	v_and_b32_e32 v1, 0xffff0000, v168
	v_fmac_f32_e32 v50, v6, v4
	v_and_b32_e32 v4, 0xffff0000, v169
	v_fmac_f32_e32 v46, v0, v1
	ds_read_b128 v[0:3], v234 offset:37504
	v_fmac_f32_e32 v51, v5, v4
	ds_read_b128 v[4:7], v234 offset:37824
	s_waitcnt lgkmcnt(1)
	s_waitcnt vmcnt(13)
	v_lshlrev_b32_e32 v8, 16, v172
	v_fmac_f32_e32 v45, v0, v8
	v_and_b32_e32 v0, 0xffff0000, v172
	v_fmac_f32_e32 v46, v1, v0
	v_lshlrev_b32_e32 v0, 16, v173
	v_fmac_f32_e32 v50, v2, v0
	v_and_b32_e32 v0, 0xffff0000, v173
	v_fmac_f32_e32 v51, v3, v0
	s_waitcnt lgkmcnt(0)
	v_mov_b32_e32 v0, v6
	v_mov_b32_e32 v1, v5
	v_mov_b32_e32 v2, v7
	s_waitcnt vmcnt(3)
	v_lshlrev_b32_e32 v3, 16, v174
	s_nop 0
	v_fmac_f32_e32 v45, v4, v3
	v_and_b32_e32 v3, 0xffff0000, v174
	v_fmac_f32_e32 v46, v1, v3
	v_lshlrev_b32_e32 v1, 16, v175
	v_fmac_f32_e32 v50, v0, v1
	v_and_b32_e32 v0, 0xffff0000, v175
	v_fmac_f32_e32 v51, v2, v0
	s_nop 0
	v_cvt_pk_bf16_f32 v36, v45, v46
	v_cvt_pk_bf16_f32 v37, v50, v51
	ds_read_b128 v[0:3], v234 offset:36896
	ds_read_b128 v[56:59], v234 offset:38176
	ds_read_b128 v[4:7], v234 offset:37216
	v_lshlrev_b32_e32 v8, 16, v38
	s_waitcnt lgkmcnt(2)
	s_waitcnt lgkmcnt(1)
	v_fma_f32 v53, v0, v8, v56
	v_and_b32_e32 v0, 0xffff0000, v38
	v_fma_f32 v54, v1, v0, v57
	v_lshlrev_b32_e32 v0, 16, v39
	v_fma_f32 v58, v2, v0, v58
	v_and_b32_e32 v0, 0xffff0000, v39
	v_fmac_f32_e32 v59, v3, v0
	s_waitcnt lgkmcnt(0)
	v_mov_b32_e32 v0, v5
	v_mov_b32_e32 v5, v7
	v_lshlrev_b32_e32 v1, 16, v164
	v_fmac_f32_e32 v53, v4, v1
	v_lshlrev_b32_e32 v4, 16, v165
	v_and_b32_e32 v1, 0xffff0000, v164
	v_fmac_f32_e32 v58, v6, v4
	v_and_b32_e32 v4, 0xffff0000, v165
	v_fmac_f32_e32 v54, v0, v1
	ds_read_b128 v[0:3], v234 offset:37536
	v_fmac_f32_e32 v59, v5, v4
	ds_read_b128 v[4:7], v234 offset:37856
	s_waitcnt lgkmcnt(1)
	v_lshlrev_b32_e32 v8, 16, v166
	v_fmac_f32_e32 v53, v0, v8
	v_and_b32_e32 v0, 0xffff0000, v166
	v_fmac_f32_e32 v54, v1, v0
	v_lshlrev_b32_e32 v0, 16, v167
	v_fmac_f32_e32 v58, v2, v0
	v_and_b32_e32 v0, 0xffff0000, v167
	v_fmac_f32_e32 v59, v3, v0
	s_waitcnt lgkmcnt(0)
	v_mov_b32_e32 v0, v4
	v_mov_b32_e32 v1, v6
	v_mov_b32_e32 v2, v5
	s_waitcnt vmcnt(2)
	v_lshlrev_b32_e32 v3, 16, v170
	v_fmac_f32_e32 v53, v0, v3
	v_and_b32_e32 v0, 0xffff0000, v170
	v_fmac_f32_e32 v54, v2, v0
	v_lshlrev_b32_e32 v0, 16, v171
	v_fmac_f32_e32 v58, v1, v0
	v_and_b32_e32 v0, 0xffff0000, v171
	v_fmac_f32_e32 v59, v7, v0
	s_nop 0
	v_cvt_pk_bf16_f32 v38, v53, v54
	v_cvt_pk_bf16_f32 v39, v58, v59
	ds_read_b128 v[0:3], v234 offset:36928
	ds_read_b128 v[64:67], v234 offset:38208
	ds_read_b128 v[4:7], v234 offset:37248
	v_lshlrev_b32_e32 v8, 16, v40
	s_waitcnt lgkmcnt(2)
	s_waitcnt lgkmcnt(1)
	v_fma_f32 v61, v0, v8, v64
	v_and_b32_e32 v0, 0xffff0000, v40
	v_fma_f32 v62, v1, v0, v65
	v_lshlrev_b32_e32 v0, 16, v41
	v_fma_f32 v66, v2, v0, v66
	v_and_b32_e32 v0, 0xffff0000, v41
	v_fmac_f32_e32 v67, v3, v0
	s_waitcnt lgkmcnt(0)
	v_mov_b32_e32 v0, v5
	v_mov_b32_e32 v5, v7
	v_lshlrev_b32_e32 v1, 16, v156
	v_fmac_f32_e32 v61, v4, v1
	v_lshlrev_b32_e32 v4, 16, v157
	v_and_b32_e32 v1, 0xffff0000, v156
	v_fmac_f32_e32 v66, v6, v4
	v_and_b32_e32 v4, 0xffff0000, v157
	v_fmac_f32_e32 v62, v0, v1
	ds_read_b128 v[0:3], v234 offset:37568
	v_fmac_f32_e32 v67, v5, v4
	ds_read_b128 v[4:7], v234 offset:37888
	s_waitcnt lgkmcnt(1)
	v_lshlrev_b32_e32 v8, 16, v160
	v_fmac_f32_e32 v61, v0, v8
	v_and_b32_e32 v0, 0xffff0000, v160
	v_fmac_f32_e32 v62, v1, v0
	v_lshlrev_b32_e32 v0, 16, v161
	v_fmac_f32_e32 v66, v2, v0
	v_and_b32_e32 v0, 0xffff0000, v161
	v_fmac_f32_e32 v67, v3, v0
	s_waitcnt lgkmcnt(0)
	v_mov_b32_e32 v0, v7
	v_mov_b32_e32 v1, v4
	v_mov_b32_e32 v2, v6
	v_lshlrev_b32_e32 v3, 16, v162
	v_fmac_f32_e32 v61, v1, v3
	v_and_b32_e32 v1, 0xffff0000, v162
	v_fmac_f32_e32 v62, v5, v1
	v_lshlrev_b32_e32 v1, 16, v163
	v_fmac_f32_e32 v66, v2, v1
	v_and_b32_e32 v1, 0xffff0000, v163
	v_fmac_f32_e32 v67, v0, v1
	s_nop 0
	v_cvt_pk_bf16_f32 v40, v61, v62
	v_cvt_pk_bf16_f32 v41, v66, v67
	ds_read_b128 v[0:3], v234 offset:36960
	ds_read_b128 v[72:75], v234 offset:38240
	ds_read_b128 v[4:7], v234 offset:37280
	v_lshlrev_b32_e32 v8, 16, v42
	s_waitcnt lgkmcnt(2)
	s_waitcnt lgkmcnt(1)
	v_fma_f32 v69, v0, v8, v72
	v_and_b32_e32 v0, 0xffff0000, v42
	v_fma_f32 v70, v1, v0, v73
	v_lshlrev_b32_e32 v0, 16, v43
	v_fma_f32 v74, v2, v0, v74
	v_and_b32_e32 v0, 0xffff0000, v43
	v_fmac_f32_e32 v75, v3, v0
	s_waitcnt lgkmcnt(0)
	v_mov_b32_e32 v0, v4
	v_mov_b32_e32 v4, v6
	v_mov_b32_e32 v1, v5
	v_lshlrev_b32_e32 v2, 16, v150
	v_lshlrev_b32_e32 v5, 16, v151
	v_fmac_f32_e32 v69, v0, v2
	v_and_b32_e32 v0, 0xffff0000, v150
	v_fmac_f32_e32 v74, v4, v5
	v_and_b32_e32 v4, 0xffff0000, v151
	v_fmac_f32_e32 v70, v1, v0
	ds_read_b128 v[0:3], v234 offset:37600
	v_fmac_f32_e32 v75, v7, v4
	ds_read_b128 v[4:7], v234 offset:37920
	s_waitcnt lgkmcnt(1)
; #define LAS __attribute__((address_space(3)))
; __device__ __forceinline__ unsigned pk2(float lo, float hi) { f32x2_t v = {lo, hi}; bf16x2_t b = __builtin_convertvector(v, bf16x2_t); return __builtin_bit_cast(unsigned, b); }
; __device__ __forceinline__ float bflo(unsigned u) { return __uint_as_float(u << 16); }
; __device__ __forceinline__ float bfhi(unsigned u) { return __uint_as_float(u & 0xffff0000u); }
; __device__ __forceinline__ void lru_phase(const Ptrs& P, LAS unsigned char* lds, int G, int wave, int lane, int tid) {
;     ...
;           for (int s = 0; s < 5; ++s) { unsigned pkd[4];
; #pragma unroll
;               for (int half = 0; half < 2; ++half) { const int ch0 = 16 * s + 8 * half;
;                   const f32x4 cb = *(const LAS f32x4*)(par + 4 * LB + ch0 + 4 * hh);
;                   float a0 = cb[0], a1 = cb[1], a2 = cb[2], a3 = cb[3];
; #pragma unroll
;                   for (int tap = 0; tap < 4; ++tap) { const v2u rw = raw[s * 2 + half][tap];
;                       const f32x4 cw = *(const LAS f32x4*)(par + tap * LB + ch0 + 4 * hh);
;                       float c0 = cw[0], c1 = cw[1], c2 = cw[2], c3 = cw[3]; asm("" : "+v"(c0), "+v"(c1), "+v"(c2), "+v"(c3));
;                       a0 = __builtin_fmaf(c0, bflo(rw.x), a0); a1 = __builtin_fmaf(c1, bfhi(rw.x), a1); a2 = __builtin_fmaf(c2, bflo(rw.y), a2); a3 = __builtin_fmaf(c3, bfhi(rw.y), a3); }
;                   asm volatile("" : "+v"(a0), "+v"(a1), "+v"(a2), "+v"(a3));
;                   xc[s][half][0] = a0; xc[s][half][1] = a1; xc[s][half][2] = a2; xc[s][half][3] = a3;
;                   pkd[2 * half] = pk2(a0, a1); pkd[2 * half + 1] = pk2(a2, a3); __builtin_amdgcn_sched_barrier(0); }
;               v4u t = {pkd[0], pkd[1], pkd[2], pkd[3]}; xf[s] = __builtin_bit_cast(bf16x8, t); __builtin_amdgcn_sched_barrier(0); } }
	v_lshlrev_b32_e32 v8, 16, v154
	v_fmac_f32_e32 v69, v0, v8
	v_and_b32_e32 v0, 0xffff0000, v154
	v_fmac_f32_e32 v70, v1, v0
	v_lshlrev_b32_e32 v0, 16, v155
	v_fmac_f32_e32 v74, v2, v0
	v_and_b32_e32 v0, 0xffff0000, v155
	v_fmac_f32_e32 v75, v3, v0
	s_waitcnt lgkmcnt(0)
	v_mov_b32_e32 v0, v7
	v_mov_b32_e32 v1, v4
	v_mov_b32_e32 v2, v6
	v_lshlrev_b32_e32 v3, 16, v158
	v_fmac_f32_e32 v69, v1, v3
	v_and_b32_e32 v1, 0xffff0000, v158
	v_fmac_f32_e32 v70, v5, v1
	v_lshlrev_b32_e32 v1, 16, v159
	v_fmac_f32_e32 v74, v2, v1
	v_and_b32_e32 v1, 0xffff0000, v159
	v_fmac_f32_e32 v75, v0, v1
	s_nop 0
	v_cvt_pk_bf16_f32 v42, v69, v70
	v_cvt_pk_bf16_f32 v43, v74, v75
	ds_read_b128 v[0:3], v234 offset:36992
	ds_read_b128 v[84:87], v234 offset:38272
	ds_read_b128 v[4:7], v234 offset:37312
	v_lshlrev_b32_e32 v8, 16, v76
	s_waitcnt lgkmcnt(2)
	s_waitcnt lgkmcnt(1)
	v_fma_f32 v81, v0, v8, v84
	v_and_b32_e32 v0, 0xffff0000, v76
	v_fma_f32 v82, v1, v0, v85
	v_lshlrev_b32_e32 v0, 16, v77
	v_fma_f32 v86, v2, v0, v86
	v_and_b32_e32 v0, 0xffff0000, v77
	v_fmac_f32_e32 v87, v3, v0
	s_waitcnt lgkmcnt(0)
	v_mov_b32_e32 v0, v4
	v_mov_b32_e32 v4, v6
	v_lshlrev_b32_e32 v1, 16, v144
	v_fmac_f32_e32 v81, v0, v1
	v_and_b32_e32 v0, 0xffff0000, v144
	v_fmac_f32_e32 v82, v5, v0
	v_lshlrev_b32_e32 v5, 16, v145
	v_fmac_f32_e32 v86, v4, v5
	v_and_b32_e32 v4, 0xffff0000, v145
	ds_read_b128 v[0:3], v234 offset:37632
	v_fmac_f32_e32 v87, v7, v4
	ds_read_b128 v[4:7], v234 offset:37952
	s_waitcnt lgkmcnt(1)
	v_lshlrev_b32_e32 v8, 16, v148
	v_fmac_f32_e32 v81, v0, v8
	v_and_b32_e32 v0, 0xffff0000, v148
	v_fmac_f32_e32 v82, v1, v0
	v_lshlrev_b32_e32 v0, 16, v149
	v_fmac_f32_e32 v86, v2, v0
	v_and_b32_e32 v0, 0xffff0000, v149
	v_fmac_f32_e32 v87, v3, v0
	s_waitcnt lgkmcnt(0)
	v_mov_b32_e32 v0, v7
	v_mov_b32_e32 v1, v4
	v_mov_b32_e32 v2, v6
	v_lshlrev_b32_e32 v3, 16, v152
	v_fmac_f32_e32 v81, v1, v3
	v_and_b32_e32 v1, 0xffff0000, v152
	v_fmac_f32_e32 v82, v5, v1
	v_lshlrev_b32_e32 v1, 16, v153
	v_fmac_f32_e32 v86, v2, v1
	v_and_b32_e32 v1, 0xffff0000, v153
	v_fmac_f32_e32 v87, v0, v1
	s_nop 0
	v_cvt_pk_bf16_f32 v76, v81, v82
	v_cvt_pk_bf16_f32 v77, v86, v87
	ds_read_b128 v[0:3], v234 offset:37024
	ds_read_b128 v[92:95], v234 offset:38304
	ds_read_b128 v[4:7], v234 offset:37344
	v_lshlrev_b32_e32 v8, 16, v78
	s_waitcnt lgkmcnt(2)
	s_waitcnt lgkmcnt(1)
	v_fma_f32 v89, v0, v8, v92
	v_and_b32_e32 v0, 0xffff0000, v78
	v_fma_f32 v90, v1, v0, v93
	v_lshlrev_b32_e32 v0, 16, v79
	v_fma_f32 v94, v2, v0, v94
	v_and_b32_e32 v0, 0xffff0000, v79
	v_fmac_f32_e32 v95, v3, v0
	s_waitcnt lgkmcnt(0)
	v_mov_b32_e32 v0, v4
	v_mov_b32_e32 v4, v6
	v_lshlrev_b32_e32 v1, 16, v126
	v_fmac_f32_e32 v89, v0, v1
	v_and_b32_e32 v0, 0xffff0000, v126
	v_fmac_f32_e32 v90, v5, v0
	v_lshlrev_b32_e32 v5, 16, v127
	v_fmac_f32_e32 v94, v4, v5
	v_and_b32_e32 v4, 0xffff0000, v127
	ds_read_b128 v[0:3], v234 offset:37664
	v_fmac_f32_e32 v95, v7, v4
	ds_read_b128 v[4:7], v234 offset:37984
	s_waitcnt lgkmcnt(1)
	v_lshlrev_b32_e32 v8, 16, v142
	v_fmac_f32_e32 v89, v0, v8
	v_and_b32_e32 v0, 0xffff0000, v142
	v_fmac_f32_e32 v90, v1, v0
	v_lshlrev_b32_e32 v0, 16, v143
	v_fmac_f32_e32 v94, v2, v0
	v_and_b32_e32 v0, 0xffff0000, v143
	v_fmac_f32_e32 v95, v3, v0
	s_waitcnt lgkmcnt(0)
	v_mov_b32_e32 v0, v7
	v_mov_b32_e32 v1, v4
	v_mov_b32_e32 v2, v6
	v_lshlrev_b32_e32 v3, 16, v146
	v_fmac_f32_e32 v89, v1, v3
	v_and_b32_e32 v1, 0xffff0000, v146
	v_fmac_f32_e32 v90, v5, v1
	v_lshlrev_b32_e32 v1, 16, v147
	v_fmac_f32_e32 v94, v2, v1
	v_and_b32_e32 v1, 0xffff0000, v147
	v_fmac_f32_e32 v95, v0, v1
	s_nop 0
	v_cvt_pk_bf16_f32 v78, v89, v90
	v_cvt_pk_bf16_f32 v79, v94, v95
	ds_read_b128 v[0:3], v234 offset:37056
	ds_read_b128 v[100:103], v234 offset:38336
	ds_read_b128 v[4:7], v234 offset:37376
	v_lshlrev_b32_e32 v8, 16, v112
	s_waitcnt lgkmcnt(2)
	s_waitcnt lgkmcnt(1)
	v_fma_f32 v97, v0, v8, v100
	v_and_b32_e32 v0, 0xffff0000, v112
	v_fma_f32 v98, v1, v0, v101
	v_lshlrev_b32_e32 v0, 16, v113
	v_fma_f32 v102, v2, v0, v102
	v_and_b32_e32 v0, 0xffff0000, v113
	v_fmac_f32_e32 v103, v3, v0
	s_waitcnt lgkmcnt(0)
	v_mov_b32_e32 v0, v4
	v_mov_b32_e32 v4, v6
	v_lshlrev_b32_e32 v1, 16, v118
	v_fmac_f32_e32 v97, v0, v1
	v_and_b32_e32 v0, 0xffff0000, v118
	v_fmac_f32_e32 v98, v5, v0
	v_lshlrev_b32_e32 v5, 16, v119
	v_fmac_f32_e32 v102, v4, v5
	v_and_b32_e32 v4, 0xffff0000, v119
	ds_read_b128 v[0:3], v234 offset:37696
	v_fmac_f32_e32 v103, v7, v4
	ds_read_b128 v[4:7], v234 offset:38016
	s_waitcnt lgkmcnt(1)
	v_lshlrev_b32_e32 v8, 16, v124
	v_fmac_f32_e32 v97, v0, v8
	v_and_b32_e32 v0, 0xffff0000, v124
	v_fmac_f32_e32 v98, v1, v0
	v_lshlrev_b32_e32 v0, 16, v125
	v_fmac_f32_e32 v102, v2, v0
	v_and_b32_e32 v0, 0xffff0000, v125
	v_fmac_f32_e32 v103, v3, v0
	s_waitcnt lgkmcnt(0)
	v_mov_b32_e32 v0, v5
	v_mov_b32_e32 v1, v7
	v_mov_b32_e32 v2, v4
	v_lshlrev_b32_e32 v3, 16, v140
	v_fmac_f32_e32 v97, v2, v3
	v_and_b32_e32 v2, 0xffff0000, v140
	v_fmac_f32_e32 v98, v0, v2
	v_lshlrev_b32_e32 v0, 16, v141
	v_fmac_f32_e32 v102, v6, v0
	v_and_b32_e32 v0, 0xffff0000, v141
	v_fmac_f32_e32 v103, v1, v0
	s_nop 0
	v_cvt_pk_bf16_f32 v112, v97, v98
	v_cvt_pk_bf16_f32 v113, v102, v103
	ds_read_b128 v[0:3], v234 offset:37088
	ds_read_b128 v[108:111], v234 offset:38368
	ds_read_b128 v[4:7], v234 offset:37408
	v_lshlrev_b32_e32 v8, 16, v28
	s_waitcnt lgkmcnt(2)
	s_waitcnt lgkmcnt(1)
	v_fma_f32 v105, v0, v8, v108
	v_and_b32_e32 v0, 0xffff0000, v28
	v_fma_f32 v106, v1, v0, v109
	v_lshlrev_b32_e32 v0, 16, v29
	v_fma_f32 v110, v2, v0, v110
	v_and_b32_e32 v0, 0xffff0000, v29
	v_fmac_f32_e32 v111, v3, v0
	s_waitcnt lgkmcnt(0)
; #define LAS __attribute__((address_space(3)))
; __device__ __forceinline__ unsigned pk2(float lo, float hi) { f32x2_t v = {lo, hi}; bf16x2_t b = __builtin_convertvector(v, bf16x2_t); return __builtin_bit_cast(unsigned, b); }
; __device__ __forceinline__ float bflo(unsigned u) { return __uint_as_float(u << 16); }
; __device__ __forceinline__ float bfhi(unsigned u) { return __uint_as_float(u & 0xffff0000u); }
; #define MFMA32(a, b, c) __builtin_amdgcn_mfma_f32_32x32x16_bf16((a), (b), (c), 0, 0, 0)
; __device__ __forceinline__ void lru_phase(const Ptrs& P, LAS unsigned char* lds, int G, int wave, int lane, int tid) {
;     ...
;           for (int s = 0; s < 5; ++s) { unsigned pkd[4];
; #pragma unroll
;               for (int half = 0; half < 2; ++half) { const int ch0 = 16 * s + 8 * half;
;                   const f32x4 cb = *(const LAS f32x4*)(par + 4 * LB + ch0 + 4 * hh);
;                   float a0 = cb[0], a1 = cb[1], a2 = cb[2], a3 = cb[3];
; #pragma unroll
;                   for (int tap = 0; tap < 4; ++tap) { const v2u rw = raw[s * 2 + half][tap];
;                       const f32x4 cw = *(const LAS f32x4*)(par + tap * LB + ch0 + 4 * hh);
;                       float c0 = cw[0], c1 = cw[1], c2 = cw[2], c3 = cw[3]; asm("" : "+v"(c0), "+v"(c1), "+v"(c2), "+v"(c3));
;                       a0 = __builtin_fmaf(c0, bflo(rw.x), a0); a1 = __builtin_fmaf(c1, bfhi(rw.x), a1); a2 = __builtin_fmaf(c2, bflo(rw.y), a2); a3 = __builtin_fmaf(c3, bfhi(rw.y), a3); }
;                   asm volatile("" : "+v"(a0), "+v"(a1), "+v"(a2), "+v"(a3));
;                   xc[s][half][0] = a0; xc[s][half][1] = a1; xc[s][half][2] = a2; xc[s][half][3] = a3;
;                   pkd[2 * half] = pk2(a0, a1); pkd[2 * half + 1] = pk2(a2, a3); __builtin_amdgcn_sched_barrier(0); }
;               v4u t = {pkd[0], pkd[1], pkd[2], pkd[3]}; xf[s] = __builtin_bit_cast(bf16x8, t); __builtin_amdgcn_sched_barrier(0); } }
;     ...
;             const LAS bf16x8* wa = (const LAS bf16x8*)(lds + L_WGF) + (size_t)(mt * 6) * 64 + lane;
;             const LAS bf16x8* wb = (const LAS bf16x8*)(lds + L_WGF) + (size_t)((3 + mt) * 6) * 64 + lane;
; #pragma unroll
;             for (int s = 0; s < 5; ++s) { gr = MFMA32(wa[s * 64], xf[s], gr); gi = MFMA32(wb[s * 64], xf[s], gi); }
;             gr = MFMA32(wa[5 * 64], xone, gr); gi = MFMA32(wb[5 * 64], xone, gi);
	v_mov_b32_e32 v0, v4
	v_mov_b32_e32 v4, v6
	v_lshlrev_b32_e32 v1, 16, v114
	v_fmac_f32_e32 v105, v0, v1
	v_and_b32_e32 v0, 0xffff0000, v114
	v_fmac_f32_e32 v106, v5, v0
	v_lshlrev_b32_e32 v5, 16, v115
	v_fmac_f32_e32 v110, v4, v5
	v_and_b32_e32 v4, 0xffff0000, v115
	ds_read_b128 v[0:3], v234 offset:37728
	v_fmac_f32_e32 v111, v7, v4
	ds_read_b128 v[4:7], v234 offset:38048
	s_waitcnt lgkmcnt(1)
	v_lshlrev_b32_e32 v8, 16, v116
	v_fmac_f32_e32 v105, v0, v8
	v_and_b32_e32 v0, 0xffff0000, v116
	v_fmac_f32_e32 v106, v1, v0
	v_lshlrev_b32_e32 v0, 16, v117
	v_fmac_f32_e32 v110, v2, v0
	v_and_b32_e32 v0, 0xffff0000, v117
	v_fmac_f32_e32 v111, v3, v0
	s_waitcnt lgkmcnt(0)
	v_mov_b32_e32 v0, v6
	v_mov_b32_e32 v1, v5
	v_mov_b32_e32 v2, v7
	v_lshlrev_b32_e32 v3, 16, v122
	s_nop 0
	v_fmac_f32_e32 v105, v4, v3
	v_and_b32_e32 v3, 0xffff0000, v122
	v_fmac_f32_e32 v106, v1, v3
	v_lshlrev_b32_e32 v1, 16, v123
	v_fmac_f32_e32 v110, v0, v1
	v_and_b32_e32 v0, 0xffff0000, v123
	v_fmac_f32_e32 v111, v2, v0
	s_nop 0
	v_cvt_pk_bf16_f32 v114, v105, v106
	v_cvt_pk_bf16_f32 v115, v110, v111
	ds_read_b128 v[0:3], v234 offset:37120
	ds_read_b128 v[116:119], v234 offset:38400
	ds_read_b128 v[4:7], v234 offset:37440
	v_lshlrev_b32_e32 v8, 16, v20
	s_waitcnt lgkmcnt(2)
	s_waitcnt lgkmcnt(1)
	v_fma_f32 v136, v0, v8, v116
	v_and_b32_e32 v0, 0xffff0000, v20
	v_fma_f32 v129, v1, v0, v117
	v_lshlrev_b32_e32 v0, 16, v21
	v_fma_f32 v116, v2, v0, v118
	v_and_b32_e32 v0, 0xffff0000, v21
	v_fmac_f32_e32 v119, v3, v0
	s_waitcnt lgkmcnt(0)
	v_mov_b32_e32 v0, v5
	v_mov_b32_e32 v5, v7
	v_mov_b32_e32 v1, v4
	v_lshlrev_b32_e32 v2, 16, v24
	v_lshlrev_b32_e32 v4, 16, v25
	v_fmac_f32_e32 v136, v1, v2
	v_and_b32_e32 v1, 0xffff0000, v24
	v_fmac_f32_e32 v116, v6, v4
	v_and_b32_e32 v4, 0xffff0000, v25
	v_fmac_f32_e32 v129, v0, v1
	ds_read_b128 v[0:3], v234 offset:37760
	v_fmac_f32_e32 v119, v5, v4
	ds_read_b128 v[4:7], v234 offset:38080
	s_waitcnt lgkmcnt(1)
	v_lshlrev_b32_e32 v8, 16, v30
	v_fmac_f32_e32 v136, v0, v8
	v_and_b32_e32 v0, 0xffff0000, v30
	v_fmac_f32_e32 v129, v1, v0
	v_lshlrev_b32_e32 v0, 16, v31
	v_fmac_f32_e32 v116, v2, v0
	v_and_b32_e32 v0, 0xffff0000, v31
	v_fmac_f32_e32 v119, v3, v0
	s_waitcnt lgkmcnt(0)
	v_mov_b32_e32 v0, v6
	v_mov_b32_e32 v1, v5
	v_mov_b32_e32 v2, v7
	s_waitcnt vmcnt(1)
	v_lshlrev_b32_e32 v3, 16, v120
	s_nop 0
	v_fmac_f32_e32 v136, v4, v3
	v_and_b32_e32 v3, 0xffff0000, v120
	v_fmac_f32_e32 v129, v1, v3
	v_lshlrev_b32_e32 v1, 16, v121
	v_fmac_f32_e32 v116, v0, v1
	v_and_b32_e32 v0, 0xffff0000, v121
	v_fmac_f32_e32 v119, v2, v0
	s_nop 0
	v_cvt_pk_bf16_f32 v124, v136, v129
	v_cvt_pk_bf16_f32 v125, v116, v119
	ds_read_b128 v[0:3], v234 offset:37152
	ds_read_b128 v[120:123], v234 offset:38432
	ds_read_b128 v[4:7], v234 offset:37472
	v_lshlrev_b32_e32 v8, 16, v16
	s_waitcnt lgkmcnt(2)
	s_waitcnt lgkmcnt(1)
	v_fma_f32 v120, v0, v8, v120
	v_and_b32_e32 v0, 0xffff0000, v16
	v_fma_f32 v118, v1, v0, v121
	v_lshlrev_b32_e32 v0, 16, v17
	v_fma_f32 v117, v2, v0, v122
	v_and_b32_e32 v0, 0xffff0000, v17
	v_fmac_f32_e32 v123, v3, v0
	s_waitcnt lgkmcnt(0)
	v_mov_b32_e32 v0, v5
	v_mov_b32_e32 v5, v7
	v_lshlrev_b32_e32 v1, 16, v18
	v_fmac_f32_e32 v120, v4, v1
	v_lshlrev_b32_e32 v4, 16, v19
	v_and_b32_e32 v1, 0xffff0000, v18
	v_fmac_f32_e32 v117, v6, v4
	v_and_b32_e32 v4, 0xffff0000, v19
	v_fmac_f32_e32 v118, v0, v1
	ds_read_b128 v[0:3], v234 offset:37792
	v_fmac_f32_e32 v123, v5, v4
	ds_read_b128 v[4:7], v234 offset:38112
	s_waitcnt lgkmcnt(1)
	v_lshlrev_b32_e32 v8, 16, v22
	v_fmac_f32_e32 v120, v0, v8
	v_and_b32_e32 v0, 0xffff0000, v22
	v_fmac_f32_e32 v118, v1, v0
	v_lshlrev_b32_e32 v0, 16, v23
	v_fmac_f32_e32 v117, v2, v0
	v_and_b32_e32 v0, 0xffff0000, v23
	v_fmac_f32_e32 v123, v3, v0
	s_waitcnt lgkmcnt(0)
	v_mov_b32_e32 v0, v4
	v_mov_b32_e32 v1, v6
	v_mov_b32_e32 v2, v5
	s_waitcnt vmcnt(0)
	v_lshlrev_b32_e32 v3, 16, v26
	v_fmac_f32_e32 v120, v0, v3
	v_and_b32_e32 v0, 0xffff0000, v26
	v_fmac_f32_e32 v118, v2, v0
	v_lshlrev_b32_e32 v0, 16, v27
	v_fmac_f32_e32 v117, v1, v0
	v_and_b32_e32 v0, 0xffff0000, v27
	v_fmac_f32_e32 v123, v7, v0
	s_nop 0
	v_cvt_pk_bf16_f32 v126, v120, v118
	v_cvt_pk_bf16_f32 v127, v117, v123
	ds_read_b128 v[0:3], v237
	ds_read_b128 v[140:143], v237 offset:1024
	ds_read_b128 v[16:19], v237 offset:18432
	ds_read_b128 v[144:147], v237 offset:19456
	s_waitcnt lgkmcnt(3)
	v_mfma_f32_32x32x16_bf16 v[0:15], v[0:3], v[36:39], 0
	s_waitcnt lgkmcnt(1)
	v_mfma_f32_32x32x16_bf16 v[16:31], v[16:19], v[36:39], 0
	v_mfma_f32_32x32x16_bf16 v[0:15], v[140:143], v[40:43], v[0:15]
	s_waitcnt lgkmcnt(0)
	v_mfma_f32_32x32x16_bf16 v[16:31], v[144:147], v[40:43], v[16:31]
	ds_read_b128 v[140:143], v237 offset:2048
	ds_read_b128 v[144:147], v237 offset:3072
	s_waitcnt lgkmcnt(1)
	v_mfma_f32_32x32x16_bf16 v[0:15], v[140:143], v[76:79], v[0:15]
	ds_read_b128 v[140:143], v237 offset:20480
	ds_read_b128 v[148:151], v237 offset:21504
	s_waitcnt lgkmcnt(1)
	v_mfma_f32_32x32x16_bf16 v[16:31], v[140:143], v[76:79], v[16:31]
	v_mfma_f32_32x32x16_bf16 v[0:15], v[144:147], v[112:115], v[0:15]
	ds_read_b128 v[140:143], v237 offset:4096
	ds_read_b128 v[144:147], v237 offset:5120
	s_waitcnt lgkmcnt(2)
	v_mfma_f32_32x32x16_bf16 v[16:31], v[148:151], v[112:115], v[16:31]
	s_waitcnt lgkmcnt(1)
	v_mfma_f32_32x32x16_bf16 v[0:15], v[140:143], v[124:127], v[0:15]
	ds_read_b128 v[140:143], v237 offset:22528
	ds_read_b128 v[148:151], v237 offset:23552
	s_waitcnt lgkmcnt(1)
	v_mfma_f32_32x32x16_bf16 v[16:31], v[140:143], v[124:127], v[16:31]
	v_mfma_f32_32x32x16_bf16 v[0:15], v[144:147], v[32:35], v[0:15]
	s_waitcnt lgkmcnt(0)
; #define LAS __attribute__((address_space(3)))
; __device__ __forceinline__ float ex2(float x) { return __builtin_amdgcn_exp2f(x); }
; __device__ __forceinline__ float rcpf_(float x) { return __builtin_amdgcn_rcpf(x); }
; __device__ __forceinline__ void lru_phase(const Ptrs& P, LAS unsigned char* lds, int G, int wave, int lane, int tid) {
;     ...
;             const LAS bf16x8* wa = (const LAS bf16x8*)(lds + L_WGF) + (size_t)(mt * 6) * 64 + lane;
;             const LAS bf16x8* wb = (const LAS bf16x8*)(lds + L_WGF) + (size_t)((3 + mt) * 6) * 64 + lane;
; #pragma unroll
;             for (int s = 0; s < 5; ++s) { gr = MFMA32(wa[s * 64], xf[s], gr); gi = MFMA32(wb[s * 64], xf[s], gi); }
;             gr = MFMA32(wa[5 * 64], xone, gr); gi = MFMA32(wb[5 * 64], xone, gi);
;             __builtin_amdgcn_sched_barrier(0);
; #pragma unroll
;             for (int i4 = 0; i4 < 4; ++i4) { if (mt == 2 && i4 >= 2) continue;
;                 const int s = 2 * mt + (i4 >> 1), half = i4 & 1, ch0 = 16 * s + 8 * half + 4 * hh;
;                 const f32x4 ls2 = *(const LAS f32x4*)(par + 7 * LB + ch0);
;                 float A4[4], B4[4];
; #pragma unroll
;                 for (int q = 0; q < 4; ++q) { const int i = 4 * i4 + q;
;                     const float rg = rcpf_(1.0f + ex2(gr[i])), ig = rcpf_(1.0f + ex2(gi[i]));
;                     const float la2 = ls2[q] * rg, a = ex2(la2), xx = (2.0f * LN2) * la2;
;                     const float poly = -xx * (1.0f + xx * (0.5f + xx * ((1.0f / 6.0f) + xx * ((1.0f / 24.0f) + xx * (1.0f / 120.0f)))));
;                     const float om = (xx > -0.25f) ? poly : (1.0f - a * a);
;                     A4[q] = a; B4[q] = __builtin_amdgcn_sqrtf(om) * (ig * xc[s][half][q]); }
;                 asm volatile("s_nop 1\n\t"
;                     LRU_DPP4("row_shr:1 row_mask:0xf bank_mask:0xf") LRU_DPP4("row_shr:2 row_mask:0xf bank_mask:0xf") LRU_DPP4("row_shr:4 row_mask:0xf bank_mask:0xf")
;                     LRU_DPP4("row_shr:8 row_mask:0xf bank_mask:0xf") LRU_DPP4("row_bcast:15 row_mask:0xa bank_mask:0xf")
;                     : "+v"(A4[0]), "+v"(A4[1]), "+v"(A4[2]), "+v"(A4[3]), "+v"(B4[0]), "+v"(B4[1]), "+v"(B4[2]), "+v"(B4[3]));
; #pragma unroll
;                 for (int q = 0; q < 4; ++q) { Av[s][half][q] = A4[q]; xc[s][half][q] = B4[q]; }
;                 __builtin_amdgcn_sched_barrier(0); }
	v_mfma_f32_32x32x16_bf16 v[16:31], v[148:151], v[32:35], v[16:31]
	ds_read_b128 v[216:219], v237 offset:6144
	ds_read_b128 v[220:223], v237 offset:24576
	s_nop 9
	ds_read_b128 v[228:231], v234 offset:39104
	v_exp_f32_e32 v0, v0
	v_exp_f32_e32 v1, v1
	v_exp_f32_e32 v2, v2
	v_exp_f32_e32 v3, v3
	v_exp_f32_e32 v16, v16
	v_exp_f32_e32 v17, v17
	v_exp_f32_e32 v18, v18
	v_exp_f32_e32 v19, v19
	s_waitcnt lgkmcnt(1)
	v_mfma_f32_32x32x16_bf16 v[144:159], v[216:219], v[36:39], 0
	ds_read_b128 v[224:227], v237 offset:7168
	v_pk_add_f32 v[0:1], v[0:1], v[240:241] op_sel_hi:[1,0]
	v_pk_add_f32 v[2:3], v[2:3], v[240:241] op_sel_hi:[1,0]
	v_pk_add_f32 v[16:17], v[16:17], v[240:241] op_sel_hi:[1,0]
	v_pk_add_f32 v[18:19], v[18:19], v[240:241] op_sel_hi:[1,0]
	v_rcp_f32_e32 v0, v0
	v_rcp_f32_e32 v1, v1
	v_rcp_f32_e32 v2, v2
	v_rcp_f32_e32 v3, v3
	s_waitcnt lgkmcnt(1)
	v_mfma_f32_32x32x16_bf16 v[160:175], v[220:223], v[36:39], 0
	ds_read_b128 v[216:219], v237 offset:25600
	v_rcp_f32_e32 v16, v16
	v_rcp_f32_e32 v17, v17
	v_rcp_f32_e32 v18, v18
	v_rcp_f32_e32 v19, v19
	v_mul_f32_e32 v200, v45, v16
	v_mul_f32_e32 v201, v46, v17
	v_mul_f32_e32 v202, v50, v18
	v_mul_f32_e32 v203, v51, v19
	s_waitcnt lgkmcnt(1)
	v_mfma_f32_32x32x16_bf16 v[144:159], v[224:227], v[40:43], v[144:159]
	ds_read_b128 v[220:223], v237 offset:8192
	s_waitcnt lgkmcnt(0)
	v_pk_mul_f32 v[0:1], v[0:1], v[228:229]
	v_pk_mul_f32 v[2:3], v[2:3], v[230:231]
	v_pk_mul_f32 v[204:205], v[0:1], v[242:243] op_sel_hi:[1,0]
	v_pk_mul_f32 v[206:207], v[2:3], v[242:243] op_sel_hi:[1,0]
	v_exp_f32_e32 v44, v0
	v_exp_f32_e32 v45, v1
	v_exp_f32_e32 v46, v2
	v_exp_f32_e32 v47, v3
	s_waitcnt lgkmcnt(1)
	v_mfma_f32_32x32x16_bf16 v[160:175], v[216:219], v[40:43], v[160:175]
	ds_read_b128 v[224:227], v237 offset:26624
	v_pk_fma_f32 v[208:209], v[204:205], v[244:245], v[238:239] op_sel_hi:[1,0,0]
	v_pk_fma_f32 v[210:211], v[206:207], v[244:245], v[238:239] op_sel_hi:[1,0,0]
	v_pk_fma_f32 v[208:209], v[204:205], v[208:209], v[246:247] op_sel_hi:[1,1,0]
	v_pk_fma_f32 v[210:211], v[206:207], v[210:211], v[246:247] op_sel_hi:[1,1,0]
	v_pk_fma_f32 v[208:209], v[204:205], v[208:209], v[248:249] op_sel_hi:[1,1,0]
	v_pk_fma_f32 v[210:211], v[206:207], v[210:211], v[248:249] op_sel_hi:[1,1,0]
	v_pk_fma_f32 v[208:209], v[204:205], v[208:209], v[240:241] op_sel_hi:[1,1,0]
	v_pk_fma_f32 v[210:211], v[206:207], v[210:211], v[240:241] op_sel_hi:[1,1,0]
	s_waitcnt lgkmcnt(1)
	v_mfma_f32_32x32x16_bf16 v[144:159], v[220:223], v[76:79], v[144:159]
	ds_read_b128 v[216:219], v237 offset:9216
	v_pk_mul_f32 v[208:209], v[208:209], v[204:205] neg_lo:[0,1] neg_hi:[0,1]
	v_pk_mul_f32 v[210:211], v[210:211], v[206:207] neg_lo:[0,1] neg_hi:[0,1]
	v_pk_fma_f32 v[212:213], v[44:45], v[44:45], v[240:241] op_sel_hi:[1,1,0] neg_lo:[1,0,0] neg_hi:[1,0,0]
	v_pk_fma_f32 v[214:215], v[46:47], v[46:47], v[240:241] op_sel_hi:[1,1,0] neg_lo:[1,0,0] neg_hi:[1,0,0]
	v_cmp_lt_f32_e64 s[70:71], s29, v204
	v_cmp_lt_f32_e64 s[72:73], s29, v205
	v_cmp_lt_f32_e64 s[74:75], s29, v206
	v_cmp_lt_f32_e64 s[76:77], s29, v207
	s_waitcnt lgkmcnt(1)
	v_mfma_f32_32x32x16_bf16 v[160:175], v[224:227], v[76:79], v[160:175]
	ds_read_b128 v[220:223], v237 offset:27648
	v_cndmask_b32_e64 v212, v212, v208, s[70:71]
	v_cndmask_b32_e64 v213, v213, v209, s[72:73]
	v_cndmask_b32_e64 v214, v214, v210, s[74:75]
	v_cndmask_b32_e64 v215, v215, v211, s[76:77]
	v_sqrt_f32_e32 v212, v212
	v_sqrt_f32_e32 v213, v213
	v_sqrt_f32_e32 v214, v214
	v_sqrt_f32_e32 v215, v215
	s_waitcnt lgkmcnt(1)
	v_mfma_f32_32x32x16_bf16 v[144:159], v[216:219], v[112:115], v[144:159]
	ds_read_b128 v[224:227], v237 offset:10240
	v_pk_mul_f32 v[48:49], v[200:201], v[212:213]
	v_pk_mul_f32 v[50:51], v[202:203], v[214:215]
	s_nop 1
	v_fmac_f32_dpp v48, v48, v44 row_shr:1 row_mask:0xf bank_mask:0xf
	v_fmac_f32_dpp v49, v49, v45 row_shr:1 row_mask:0xf bank_mask:0xf
	v_fmac_f32_dpp v50, v50, v46 row_shr:1 row_mask:0xf bank_mask:0xf
	v_fmac_f32_dpp v51, v51, v47 row_shr:1 row_mask:0xf bank_mask:0xf
	v_mul_f32_dpp v44, v44, v44 row_shr:1 row_mask:0xf bank_mask:0xf
	v_mul_f32_dpp v45, v45, v45 row_shr:1 row_mask:0xf bank_mask:0xf
	s_waitcnt lgkmcnt(1)
	v_mfma_f32_32x32x16_bf16 v[160:175], v[220:223], v[112:115], v[160:175]
	ds_read_b128 v[216:219], v237 offset:28672
	v_mul_f32_dpp v46, v46, v46 row_shr:1 row_mask:0xf bank_mask:0xf
	v_mul_f32_dpp v47, v47, v47 row_shr:1 row_mask:0xf bank_mask:0xf
	v_fmac_f32_dpp v48, v48, v44 row_shr:2 row_mask:0xf bank_mask:0xf
	v_fmac_f32_dpp v49, v49, v45 row_shr:2 row_mask:0xf bank_mask:0xf
	v_fmac_f32_dpp v50, v50, v46 row_shr:2 row_mask:0xf bank_mask:0xf
	v_fmac_f32_dpp v51, v51, v47 row_shr:2 row_mask:0xf bank_mask:0xf
	v_mul_f32_dpp v44, v44, v44 row_shr:2 row_mask:0xf bank_mask:0xf
	v_mul_f32_dpp v45, v45, v45 row_shr:2 row_mask:0xf bank_mask:0xf
	s_waitcnt lgkmcnt(1)
	v_mfma_f32_32x32x16_bf16 v[144:159], v[224:227], v[124:127], v[144:159]
	ds_read_b128 v[220:223], v237 offset:11264
	v_mul_f32_dpp v46, v46, v46 row_shr:2 row_mask:0xf bank_mask:0xf
	v_mul_f32_dpp v47, v47, v47 row_shr:2 row_mask:0xf bank_mask:0xf
	v_fmac_f32_dpp v48, v48, v44 row_shr:4 row_mask:0xf bank_mask:0xf
	v_fmac_f32_dpp v49, v49, v45 row_shr:4 row_mask:0xf bank_mask:0xf
	v_fmac_f32_dpp v50, v50, v46 row_shr:4 row_mask:0xf bank_mask:0xf
	v_fmac_f32_dpp v51, v51, v47 row_shr:4 row_mask:0xf bank_mask:0xf
	v_mul_f32_dpp v44, v44, v44 row_shr:4 row_mask:0xf bank_mask:0xf
	v_mul_f32_dpp v45, v45, v45 row_shr:4 row_mask:0xf bank_mask:0xf
	s_waitcnt lgkmcnt(1)
; #define LAS __attribute__((address_space(3)))
; __device__ __forceinline__ void lru_phase(const Ptrs& P, LAS unsigned char* lds, int G, int wave, int lane, int tid) {
;     ...
;         for (int mt = 0; mt < 3; ++mt) {
;             f32x16 gr, gi;
; #pragma unroll
;             for (int i = 0; i < 16; ++i) { gr[i] = 0.f; gi[i] = 0.f; }
;             const LAS bf16x8* wa = (const LAS bf16x8*)(lds + L_WGF) + (size_t)(mt * 6) * 64 + lane;
;             const LAS bf16x8* wb = (const LAS bf16x8*)(lds + L_WGF) + (size_t)((3 + mt) * 6) * 64 + lane;
; #pragma unroll
;             for (int s = 0; s < 5; ++s) { gr = MFMA32(wa[s * 64], xf[s], gr); gi = MFMA32(wb[s * 64], xf[s], gi); }
;             gr = MFMA32(wa[5 * 64], xone, gr); gi = MFMA32(wb[5 * 64], xone, gi);
;             __builtin_amdgcn_sched_barrier(0);
; #pragma unroll
;             for (int i4 = 0; i4 < 4; ++i4) { if (mt == 2 && i4 >= 2) continue;
;                 const int s = 2 * mt + (i4 >> 1), half = i4 & 1, ch0 = 16 * s + 8 * half + 4 * hh;
;                 const f32x4 ls2 = *(const LAS f32x4*)(par + 7 * LB + ch0);
;                 float A4[4], B4[4];
; #pragma unroll
;                 for (int q = 0; q < 4; ++q) { const int i = 4 * i4 + q;
;                     const float rg = rcpf_(1.0f + ex2(gr[i])), ig = rcpf_(1.0f + ex2(gi[i]));
;                     const float la2 = ls2[q] * rg, a = ex2(la2), xx = (2.0f * LN2) * la2;
;                     const float poly = -xx * (1.0f + xx * (0.5f + xx * ((1.0f / 6.0f) + xx * ((1.0f / 24.0f) + xx * (1.0f / 120.0f)))));
;                     const float om = (xx > -0.25f) ? poly : (1.0f - a * a);
;                     A4[q] = a; B4[q] = __builtin_amdgcn_sqrtf(om) * (ig * xc[s][half][q]); }
;                 asm volatile("s_nop 1\n\t"
;                     LRU_DPP4("row_shr:1 row_mask:0xf bank_mask:0xf") LRU_DPP4("row_shr:2 row_mask:0xf bank_mask:0xf") LRU_DPP4("row_shr:4 row_mask:0xf bank_mask:0xf")
;                     LRU_DPP4("row_shr:8 row_mask:0xf bank_mask:0xf") LRU_DPP4("row_bcast:15 row_mask:0xa bank_mask:0xf")
;                     : "+v"(A4[0]), "+v"(A4[1]), "+v"(A4[2]), "+v"(A4[3]), "+v"(B4[0]), "+v"(B4[1]), "+v"(B4[2]), "+v"(B4[3]));
; #pragma unroll
;                 for (int q = 0; q < 4; ++q) { Av[s][half][q] = A4[q]; xc[s][half][q] = B4[q]; }
;                 __builtin_amdgcn_sched_barrier(0); }
	v_mfma_f32_32x32x16_bf16 v[160:175], v[216:219], v[124:127], v[160:175]
	ds_read_b128 v[224:227], v237 offset:29696
	v_mul_f32_dpp v46, v46, v46 row_shr:4 row_mask:0xf bank_mask:0xf
	v_mul_f32_dpp v47, v47, v47 row_shr:4 row_mask:0xf bank_mask:0xf
	v_fmac_f32_dpp v48, v48, v44 row_shr:8 row_mask:0xf bank_mask:0xf
	v_fmac_f32_dpp v49, v49, v45 row_shr:8 row_mask:0xf bank_mask:0xf
	v_fmac_f32_dpp v50, v50, v46 row_shr:8 row_mask:0xf bank_mask:0xf
	v_fmac_f32_dpp v51, v51, v47 row_shr:8 row_mask:0xf bank_mask:0xf
	v_mul_f32_dpp v44, v44, v44 row_shr:8 row_mask:0xf bank_mask:0xf
	v_mul_f32_dpp v45, v45, v45 row_shr:8 row_mask:0xf bank_mask:0xf
	s_waitcnt lgkmcnt(1)
	v_mfma_f32_32x32x16_bf16 v[144:159], v[220:223], v[32:35], v[144:159]
	v_mul_f32_dpp v46, v46, v46 row_shr:8 row_mask:0xf bank_mask:0xf
	v_mul_f32_dpp v47, v47, v47 row_shr:8 row_mask:0xf bank_mask:0xf
	v_fmac_f32_dpp v48, v48, v44 row_bcast:15 row_mask:0xa bank_mask:0xf
	v_fmac_f32_dpp v49, v49, v45 row_bcast:15 row_mask:0xa bank_mask:0xf
	v_fmac_f32_dpp v50, v50, v46 row_bcast:15 row_mask:0xa bank_mask:0xf
	v_fmac_f32_dpp v51, v51, v47 row_bcast:15 row_mask:0xa bank_mask:0xf
	v_mul_f32_dpp v44, v44, v44 row_bcast:15 row_mask:0xa bank_mask:0xf
	v_mul_f32_dpp v45, v45, v45 row_bcast:15 row_mask:0xa bank_mask:0xf
	s_waitcnt lgkmcnt(0)
	v_mfma_f32_32x32x16_bf16 v[160:175], v[224:227], v[32:35], v[160:175]
	v_mul_f32_dpp v46, v46, v46 row_bcast:15 row_mask:0xa bank_mask:0xf
	v_mul_f32_dpp v47, v47, v47 row_bcast:15 row_mask:0xa bank_mask:0xf
	ds_read_b128 v[228:231], v234 offset:39136
	v_exp_f32_e32 v4, v4
	v_exp_f32_e32 v5, v5
	v_exp_f32_e32 v6, v6
	v_exp_f32_e32 v7, v7
	v_exp_f32_e32 v20, v20
	v_exp_f32_e32 v21, v21
	v_exp_f32_e32 v22, v22
	v_exp_f32_e32 v23, v23
	v_pk_add_f32 v[4:5], v[4:5], v[240:241] op_sel_hi:[1,0]
	v_pk_add_f32 v[6:7], v[6:7], v[240:241] op_sel_hi:[1,0]
	v_pk_add_f32 v[20:21], v[20:21], v[240:241] op_sel_hi:[1,0]
	v_pk_add_f32 v[22:23], v[22:23], v[240:241] op_sel_hi:[1,0]
	v_rcp_f32_e32 v4, v4
	v_rcp_f32_e32 v5, v5
	v_rcp_f32_e32 v6, v6
	v_rcp_f32_e32 v7, v7
	v_rcp_f32_e32 v20, v20
	v_rcp_f32_e32 v21, v21
	v_rcp_f32_e32 v22, v22
	v_rcp_f32_e32 v23, v23
	v_mul_f32_e32 v200, v53, v20
	v_mul_f32_e32 v201, v54, v21
	v_mul_f32_e32 v202, v58, v22
	v_mul_f32_e32 v203, v59, v23
	s_waitcnt lgkmcnt(0)
	v_pk_mul_f32 v[4:5], v[4:5], v[228:229]
	v_pk_mul_f32 v[6:7], v[6:7], v[230:231]
	v_pk_mul_f32 v[204:205], v[4:5], v[242:243] op_sel_hi:[1,0]
	v_pk_mul_f32 v[206:207], v[6:7], v[242:243] op_sel_hi:[1,0]
	v_exp_f32_e32 v52, v4
	v_exp_f32_e32 v53, v5
	v_exp_f32_e32 v54, v6
	v_exp_f32_e32 v55, v7
	v_pk_fma_f32 v[208:209], v[204:205], v[244:245], v[238:239] op_sel_hi:[1,0,0]
	v_pk_fma_f32 v[210:211], v[206:207], v[244:245], v[238:239] op_sel_hi:[1,0,0]
	v_pk_fma_f32 v[208:209], v[204:205], v[208:209], v[246:247] op_sel_hi:[1,1,0]
	v_pk_fma_f32 v[210:211], v[206:207], v[210:211], v[246:247] op_sel_hi:[1,1,0]
	v_pk_fma_f32 v[208:209], v[204:205], v[208:209], v[248:249] op_sel_hi:[1,1,0]
	v_pk_fma_f32 v[210:211], v[206:207], v[210:211], v[248:249] op_sel_hi:[1,1,0]
	v_pk_fma_f32 v[208:209], v[204:205], v[208:209], v[240:241] op_sel_hi:[1,1,0]
	v_pk_fma_f32 v[210:211], v[206:207], v[210:211], v[240:241] op_sel_hi:[1,1,0]
	v_pk_mul_f32 v[208:209], v[208:209], v[204:205] neg_lo:[0,1] neg_hi:[0,1]
	v_pk_mul_f32 v[210:211], v[210:211], v[206:207] neg_lo:[0,1] neg_hi:[0,1]
	v_pk_fma_f32 v[212:213], v[52:53], v[52:53], v[240:241] op_sel_hi:[1,1,0] neg_lo:[1,0,0] neg_hi:[1,0,0]
	v_pk_fma_f32 v[214:215], v[54:55], v[54:55], v[240:241] op_sel_hi:[1,1,0] neg_lo:[1,0,0] neg_hi:[1,0,0]
	v_cmp_lt_f32_e64 s[70:71], s29, v204
	v_cmp_lt_f32_e64 s[72:73], s29, v205
	v_cmp_lt_f32_e64 s[74:75], s29, v206
	v_cmp_lt_f32_e64 s[76:77], s29, v207
	v_cndmask_b32_e64 v212, v212, v208, s[70:71]
	v_cndmask_b32_e64 v213, v213, v209, s[72:73]
	v_cndmask_b32_e64 v214, v214, v210, s[74:75]
	v_cndmask_b32_e64 v215, v215, v211, s[76:77]
	v_sqrt_f32_e32 v212, v212
	v_sqrt_f32_e32 v213, v213
	v_sqrt_f32_e32 v214, v214
	v_sqrt_f32_e32 v215, v215
	v_pk_mul_f32 v[56:57], v[200:201], v[212:213]
	v_pk_mul_f32 v[58:59], v[202:203], v[214:215]
	s_nop 1
	v_fmac_f32_dpp v56, v56, v52 row_shr:1 row_mask:0xf bank_mask:0xf
	v_fmac_f32_dpp v57, v57, v53 row_shr:1 row_mask:0xf bank_mask:0xf
	v_fmac_f32_dpp v58, v58, v54 row_shr:1 row_mask:0xf bank_mask:0xf
	v_fmac_f32_dpp v59, v59, v55 row_shr:1 row_mask:0xf bank_mask:0xf
	v_mul_f32_dpp v52, v52, v52 row_shr:1 row_mask:0xf bank_mask:0xf
	v_mul_f32_dpp v53, v53, v53 row_shr:1 row_mask:0xf bank_mask:0xf
	v_mul_f32_dpp v54, v54, v54 row_shr:1 row_mask:0xf bank_mask:0xf
	v_mul_f32_dpp v55, v55, v55 row_shr:1 row_mask:0xf bank_mask:0xf
	v_fmac_f32_dpp v56, v56, v52 row_shr:2 row_mask:0xf bank_mask:0xf
	v_fmac_f32_dpp v57, v57, v53 row_shr:2 row_mask:0xf bank_mask:0xf
	v_fmac_f32_dpp v58, v58, v54 row_shr:2 row_mask:0xf bank_mask:0xf
	v_fmac_f32_dpp v59, v59, v55 row_shr:2 row_mask:0xf bank_mask:0xf
	v_mul_f32_dpp v52, v52, v52 row_shr:2 row_mask:0xf bank_mask:0xf
	v_mul_f32_dpp v53, v53, v53 row_shr:2 row_mask:0xf bank_mask:0xf
	v_mul_f32_dpp v54, v54, v54 row_shr:2 row_mask:0xf bank_mask:0xf
	v_mul_f32_dpp v55, v55, v55 row_shr:2 row_mask:0xf bank_mask:0xf
	v_fmac_f32_dpp v56, v56, v52 row_shr:4 row_mask:0xf bank_mask:0xf
	v_fmac_f32_dpp v57, v57, v53 row_shr:4 row_mask:0xf bank_mask:0xf
	v_fmac_f32_dpp v58, v58, v54 row_shr:4 row_mask:0xf bank_mask:0xf
	v_fmac_f32_dpp v59, v59, v55 row_shr:4 row_mask:0xf bank_mask:0xf
	v_mul_f32_dpp v52, v52, v52 row_shr:4 row_mask:0xf bank_mask:0xf
	v_mul_f32_dpp v53, v53, v53 row_shr:4 row_mask:0xf bank_mask:0xf
; #define LAS __attribute__((address_space(3)))
; __device__ __forceinline__ void lru_phase(const Ptrs& P, LAS unsigned char* lds, int G, int wave, int lane, int tid) {
;     ...
;         for (int mt = 0; mt < 3; ++mt) {
;             f32x16 gr, gi;
; #pragma unroll
;             for (int i = 0; i < 16; ++i) { gr[i] = 0.f; gi[i] = 0.f; }
;             const LAS bf16x8* wa = (const LAS bf16x8*)(lds + L_WGF) + (size_t)(mt * 6) * 64 + lane;
;             const LAS bf16x8* wb = (const LAS bf16x8*)(lds + L_WGF) + (size_t)((3 + mt) * 6) * 64 + lane;
; #pragma unroll
;             for (int s = 0; s < 5; ++s) { gr = MFMA32(wa[s * 64], xf[s], gr); gi = MFMA32(wb[s * 64], xf[s], gi); }
;             gr = MFMA32(wa[5 * 64], xone, gr); gi = MFMA32(wb[5 * 64], xone, gi);
;             __builtin_amdgcn_sched_barrier(0);
; #pragma unroll
;             for (int i4 = 0; i4 < 4; ++i4) { if (mt == 2 && i4 >= 2) continue;
;                 const int s = 2 * mt + (i4 >> 1), half = i4 & 1, ch0 = 16 * s + 8 * half + 4 * hh;
;                 const f32x4 ls2 = *(const LAS f32x4*)(par + 7 * LB + ch0);
;                 float A4[4], B4[4];
; #pragma unroll
;                 for (int q = 0; q < 4; ++q) { const int i = 4 * i4 + q;
;                     const float rg = rcpf_(1.0f + ex2(gr[i])), ig = rcpf_(1.0f + ex2(gi[i]));
;                     const float la2 = ls2[q] * rg, a = ex2(la2), xx = (2.0f * LN2) * la2;
;                     const float poly = -xx * (1.0f + xx * (0.5f + xx * ((1.0f / 6.0f) + xx * ((1.0f / 24.0f) + xx * (1.0f / 120.0f)))));
;                     const float om = (xx > -0.25f) ? poly : (1.0f - a * a);
;                     A4[q] = a; B4[q] = __builtin_amdgcn_sqrtf(om) * (ig * xc[s][half][q]); }
;                 asm volatile("s_nop 1\n\t"
;                     LRU_DPP4("row_shr:1 row_mask:0xf bank_mask:0xf") LRU_DPP4("row_shr:2 row_mask:0xf bank_mask:0xf") LRU_DPP4("row_shr:4 row_mask:0xf bank_mask:0xf")
;                     LRU_DPP4("row_shr:8 row_mask:0xf bank_mask:0xf") LRU_DPP4("row_bcast:15 row_mask:0xa bank_mask:0xf")
;                     : "+v"(A4[0]), "+v"(A4[1]), "+v"(A4[2]), "+v"(A4[3]), "+v"(B4[0]), "+v"(B4[1]), "+v"(B4[2]), "+v"(B4[3]));
; #pragma unroll
;                 for (int q = 0; q < 4; ++q) { Av[s][half][q] = A4[q]; xc[s][half][q] = B4[q]; }
;                 __builtin_amdgcn_sched_barrier(0); }
	v_mul_f32_dpp v54, v54, v54 row_shr:4 row_mask:0xf bank_mask:0xf
	v_mul_f32_dpp v55, v55, v55 row_shr:4 row_mask:0xf bank_mask:0xf
	v_fmac_f32_dpp v56, v56, v52 row_shr:8 row_mask:0xf bank_mask:0xf
	v_fmac_f32_dpp v57, v57, v53 row_shr:8 row_mask:0xf bank_mask:0xf
	v_fmac_f32_dpp v58, v58, v54 row_shr:8 row_mask:0xf bank_mask:0xf
	v_fmac_f32_dpp v59, v59, v55 row_shr:8 row_mask:0xf bank_mask:0xf
	v_mul_f32_dpp v52, v52, v52 row_shr:8 row_mask:0xf bank_mask:0xf
	v_mul_f32_dpp v53, v53, v53 row_shr:8 row_mask:0xf bank_mask:0xf
	v_mul_f32_dpp v54, v54, v54 row_shr:8 row_mask:0xf bank_mask:0xf
	v_mul_f32_dpp v55, v55, v55 row_shr:8 row_mask:0xf bank_mask:0xf
	v_fmac_f32_dpp v56, v56, v52 row_bcast:15 row_mask:0xa bank_mask:0xf
	v_fmac_f32_dpp v57, v57, v53 row_bcast:15 row_mask:0xa bank_mask:0xf
	v_fmac_f32_dpp v58, v58, v54 row_bcast:15 row_mask:0xa bank_mask:0xf
	v_fmac_f32_dpp v59, v59, v55 row_bcast:15 row_mask:0xa bank_mask:0xf
	v_mul_f32_dpp v52, v52, v52 row_bcast:15 row_mask:0xa bank_mask:0xf
	v_mul_f32_dpp v53, v53, v53 row_bcast:15 row_mask:0xa bank_mask:0xf
	v_mul_f32_dpp v54, v54, v54 row_bcast:15 row_mask:0xa bank_mask:0xf
	v_mul_f32_dpp v55, v55, v55 row_bcast:15 row_mask:0xa bank_mask:0xf
	ds_read_b128 v[228:231], v234 offset:39168
	v_exp_f32_e32 v8, v8
	v_exp_f32_e32 v9, v9
	v_exp_f32_e32 v10, v10
	v_exp_f32_e32 v11, v11
	v_exp_f32_e32 v24, v24
	v_exp_f32_e32 v25, v25
	v_exp_f32_e32 v26, v26
	v_exp_f32_e32 v27, v27
	v_pk_add_f32 v[8:9], v[8:9], v[240:241] op_sel_hi:[1,0]
	v_pk_add_f32 v[10:11], v[10:11], v[240:241] op_sel_hi:[1,0]
	v_pk_add_f32 v[24:25], v[24:25], v[240:241] op_sel_hi:[1,0]
	v_pk_add_f32 v[26:27], v[26:27], v[240:241] op_sel_hi:[1,0]
	v_rcp_f32_e32 v8, v8
	v_rcp_f32_e32 v9, v9
	v_rcp_f32_e32 v10, v10
	v_rcp_f32_e32 v11, v11
	v_rcp_f32_e32 v24, v24
	v_rcp_f32_e32 v25, v25
	v_rcp_f32_e32 v26, v26
	v_rcp_f32_e32 v27, v27
	v_mul_f32_e32 v200, v61, v24
	v_mul_f32_e32 v201, v62, v25
	v_mul_f32_e32 v202, v66, v26
	v_mul_f32_e32 v203, v67, v27
	s_waitcnt lgkmcnt(0)
	v_pk_mul_f32 v[8:9], v[8:9], v[228:229]
	v_pk_mul_f32 v[10:11], v[10:11], v[230:231]
	v_pk_mul_f32 v[204:205], v[8:9], v[242:243] op_sel_hi:[1,0]
	v_pk_mul_f32 v[206:207], v[10:11], v[242:243] op_sel_hi:[1,0]
	v_exp_f32_e32 v60, v8
	v_exp_f32_e32 v61, v9
	v_exp_f32_e32 v62, v10
	v_exp_f32_e32 v63, v11
	v_pk_fma_f32 v[208:209], v[204:205], v[244:245], v[238:239] op_sel_hi:[1,0,0]
	v_pk_fma_f32 v[210:211], v[206:207], v[244:245], v[238:239] op_sel_hi:[1,0,0]
	v_pk_fma_f32 v[208:209], v[204:205], v[208:209], v[246:247] op_sel_hi:[1,1,0]
	v_pk_fma_f32 v[210:211], v[206:207], v[210:211], v[246:247] op_sel_hi:[1,1,0]
	v_pk_fma_f32 v[208:209], v[204:205], v[208:209], v[248:249] op_sel_hi:[1,1,0]
	v_pk_fma_f32 v[210:211], v[206:207], v[210:211], v[248:249] op_sel_hi:[1,1,0]
	v_pk_fma_f32 v[208:209], v[204:205], v[208:209], v[240:241] op_sel_hi:[1,1,0]
	v_pk_fma_f32 v[210:211], v[206:207], v[210:211], v[240:241] op_sel_hi:[1,1,0]
	v_pk_mul_f32 v[208:209], v[208:209], v[204:205] neg_lo:[0,1] neg_hi:[0,1]
	v_pk_mul_f32 v[210:211], v[210:211], v[206:207] neg_lo:[0,1] neg_hi:[0,1]
	v_pk_fma_f32 v[212:213], v[60:61], v[60:61], v[240:241] op_sel_hi:[1,1,0] neg_lo:[1,0,0] neg_hi:[1,0,0]
	v_pk_fma_f32 v[214:215], v[62:63], v[62:63], v[240:241] op_sel_hi:[1,1,0] neg_lo:[1,0,0] neg_hi:[1,0,0]
	v_cmp_lt_f32_e64 s[70:71], s29, v204
	v_cmp_lt_f32_e64 s[72:73], s29, v205
	v_cmp_lt_f32_e64 s[74:75], s29, v206
	v_cmp_lt_f32_e64 s[76:77], s29, v207
	v_cndmask_b32_e64 v212, v212, v208, s[70:71]
	v_cndmask_b32_e64 v213, v213, v209, s[72:73]
	v_cndmask_b32_e64 v214, v214, v210, s[74:75]
	v_cndmask_b32_e64 v215, v215, v211, s[76:77]
	v_sqrt_f32_e32 v212, v212
	v_sqrt_f32_e32 v213, v213
	v_sqrt_f32_e32 v214, v214
	v_sqrt_f32_e32 v215, v215
	v_pk_mul_f32 v[64:65], v[200:201], v[212:213]
	v_pk_mul_f32 v[66:67], v[202:203], v[214:215]
	s_nop 1
	v_fmac_f32_dpp v64, v64, v60 row_shr:1 row_mask:0xf bank_mask:0xf
	v_fmac_f32_dpp v65, v65, v61 row_shr:1 row_mask:0xf bank_mask:0xf
	v_fmac_f32_dpp v66, v66, v62 row_shr:1 row_mask:0xf bank_mask:0xf
	v_fmac_f32_dpp v67, v67, v63 row_shr:1 row_mask:0xf bank_mask:0xf
	v_mul_f32_dpp v60, v60, v60 row_shr:1 row_mask:0xf bank_mask:0xf
	v_mul_f32_dpp v61, v61, v61 row_shr:1 row_mask:0xf bank_mask:0xf
	v_mul_f32_dpp v62, v62, v62 row_shr:1 row_mask:0xf bank_mask:0xf
	v_mul_f32_dpp v63, v63, v63 row_shr:1 row_mask:0xf bank_mask:0xf
	v_fmac_f32_dpp v64, v64, v60 row_shr:2 row_mask:0xf bank_mask:0xf
	v_fmac_f32_dpp v65, v65, v61 row_shr:2 row_mask:0xf bank_mask:0xf
	v_fmac_f32_dpp v66, v66, v62 row_shr:2 row_mask:0xf bank_mask:0xf
	v_fmac_f32_dpp v67, v67, v63 row_shr:2 row_mask:0xf bank_mask:0xf
	v_mul_f32_dpp v60, v60, v60 row_shr:2 row_mask:0xf bank_mask:0xf
	v_mul_f32_dpp v61, v61, v61 row_shr:2 row_mask:0xf bank_mask:0xf
	v_mul_f32_dpp v62, v62, v62 row_shr:2 row_mask:0xf bank_mask:0xf
	v_mul_f32_dpp v63, v63, v63 row_shr:2 row_mask:0xf bank_mask:0xf
	v_fmac_f32_dpp v64, v64, v60 row_shr:4 row_mask:0xf bank_mask:0xf
	v_fmac_f32_dpp v65, v65, v61 row_shr:4 row_mask:0xf bank_mask:0xf
	v_fmac_f32_dpp v66, v66, v62 row_shr:4 row_mask:0xf bank_mask:0xf
	v_fmac_f32_dpp v67, v67, v63 row_shr:4 row_mask:0xf bank_mask:0xf
	v_mul_f32_dpp v60, v60, v60 row_shr:4 row_mask:0xf bank_mask:0xf
	v_mul_f32_dpp v61, v61, v61 row_shr:4 row_mask:0xf bank_mask:0xf
	v_mul_f32_dpp v62, v62, v62 row_shr:4 row_mask:0xf bank_mask:0xf
	v_mul_f32_dpp v63, v63, v63 row_shr:4 row_mask:0xf bank_mask:0xf
	v_fmac_f32_dpp v64, v64, v60 row_shr:8 row_mask:0xf bank_mask:0xf
	v_fmac_f32_dpp v65, v65, v61 row_shr:8 row_mask:0xf bank_mask:0xf
	v_fmac_f32_dpp v66, v66, v62 row_shr:8 row_mask:0xf bank_mask:0xf
; #define LAS __attribute__((address_space(3)))
; __device__ __forceinline__ void lru_phase(const Ptrs& P, LAS unsigned char* lds, int G, int wave, int lane, int tid) {
;     ...
;         for (int mt = 0; mt < 3; ++mt) {
;             f32x16 gr, gi;
; #pragma unroll
;             for (int i = 0; i < 16; ++i) { gr[i] = 0.f; gi[i] = 0.f; }
;             const LAS bf16x8* wa = (const LAS bf16x8*)(lds + L_WGF) + (size_t)(mt * 6) * 64 + lane;
;             const LAS bf16x8* wb = (const LAS bf16x8*)(lds + L_WGF) + (size_t)((3 + mt) * 6) * 64 + lane;
; #pragma unroll
;             for (int s = 0; s < 5; ++s) { gr = MFMA32(wa[s * 64], xf[s], gr); gi = MFMA32(wb[s * 64], xf[s], gi); }
;             gr = MFMA32(wa[5 * 64], xone, gr); gi = MFMA32(wb[5 * 64], xone, gi);
;             __builtin_amdgcn_sched_barrier(0);
; #pragma unroll
;             for (int i4 = 0; i4 < 4; ++i4) { if (mt == 2 && i4 >= 2) continue;
;                 const int s = 2 * mt + (i4 >> 1), half = i4 & 1, ch0 = 16 * s + 8 * half + 4 * hh;
;                 const f32x4 ls2 = *(const LAS f32x4*)(par + 7 * LB + ch0);
;                 float A4[4], B4[4];
; #pragma unroll
;                 for (int q = 0; q < 4; ++q) { const int i = 4 * i4 + q;
;                     const float rg = rcpf_(1.0f + ex2(gr[i])), ig = rcpf_(1.0f + ex2(gi[i]));
;                     const float la2 = ls2[q] * rg, a = ex2(la2), xx = (2.0f * LN2) * la2;
;                     const float poly = -xx * (1.0f + xx * (0.5f + xx * ((1.0f / 6.0f) + xx * ((1.0f / 24.0f) + xx * (1.0f / 120.0f)))));
;                     const float om = (xx > -0.25f) ? poly : (1.0f - a * a);
;                     A4[q] = a; B4[q] = __builtin_amdgcn_sqrtf(om) * (ig * xc[s][half][q]); }
;                 asm volatile("s_nop 1\n\t"
;                     LRU_DPP4("row_shr:1 row_mask:0xf bank_mask:0xf") LRU_DPP4("row_shr:2 row_mask:0xf bank_mask:0xf") LRU_DPP4("row_shr:4 row_mask:0xf bank_mask:0xf")
;                     LRU_DPP4("row_shr:8 row_mask:0xf bank_mask:0xf") LRU_DPP4("row_bcast:15 row_mask:0xa bank_mask:0xf")
;                     : "+v"(A4[0]), "+v"(A4[1]), "+v"(A4[2]), "+v"(A4[3]), "+v"(B4[0]), "+v"(B4[1]), "+v"(B4[2]), "+v"(B4[3]));
; #pragma unroll
;                 for (int q = 0; q < 4; ++q) { Av[s][half][q] = A4[q]; xc[s][half][q] = B4[q]; }
;                 __builtin_amdgcn_sched_barrier(0); }
	v_fmac_f32_dpp v67, v67, v63 row_shr:8 row_mask:0xf bank_mask:0xf
	v_mul_f32_dpp v60, v60, v60 row_shr:8 row_mask:0xf bank_mask:0xf
	v_mul_f32_dpp v61, v61, v61 row_shr:8 row_mask:0xf bank_mask:0xf
	v_mul_f32_dpp v62, v62, v62 row_shr:8 row_mask:0xf bank_mask:0xf
	v_mul_f32_dpp v63, v63, v63 row_shr:8 row_mask:0xf bank_mask:0xf
	v_fmac_f32_dpp v64, v64, v60 row_bcast:15 row_mask:0xa bank_mask:0xf
	v_fmac_f32_dpp v65, v65, v61 row_bcast:15 row_mask:0xa bank_mask:0xf
	v_fmac_f32_dpp v66, v66, v62 row_bcast:15 row_mask:0xa bank_mask:0xf
	v_fmac_f32_dpp v67, v67, v63 row_bcast:15 row_mask:0xa bank_mask:0xf
	v_mul_f32_dpp v60, v60, v60 row_bcast:15 row_mask:0xa bank_mask:0xf
	v_mul_f32_dpp v61, v61, v61 row_bcast:15 row_mask:0xa bank_mask:0xf
	v_mul_f32_dpp v62, v62, v62 row_bcast:15 row_mask:0xa bank_mask:0xf
	v_mul_f32_dpp v63, v63, v63 row_bcast:15 row_mask:0xa bank_mask:0xf
	ds_read_b128 v[228:231], v234 offset:39200
	v_exp_f32_e32 v12, v12
	v_exp_f32_e32 v13, v13
	v_exp_f32_e32 v14, v14
	v_exp_f32_e32 v15, v15
	v_exp_f32_e32 v28, v28
	v_exp_f32_e32 v29, v29
	v_exp_f32_e32 v30, v30
	v_exp_f32_e32 v31, v31
	v_pk_add_f32 v[12:13], v[12:13], v[240:241] op_sel_hi:[1,0]
	v_pk_add_f32 v[14:15], v[14:15], v[240:241] op_sel_hi:[1,0]
	v_pk_add_f32 v[28:29], v[28:29], v[240:241] op_sel_hi:[1,0]
	v_pk_add_f32 v[30:31], v[30:31], v[240:241] op_sel_hi:[1,0]
	v_rcp_f32_e32 v12, v12
	v_rcp_f32_e32 v13, v13
	v_rcp_f32_e32 v14, v14
	v_rcp_f32_e32 v15, v15
	v_rcp_f32_e32 v28, v28
	v_rcp_f32_e32 v29, v29
	v_rcp_f32_e32 v30, v30
	v_rcp_f32_e32 v31, v31
	v_mul_f32_e32 v200, v69, v28
	v_mul_f32_e32 v201, v70, v29
	v_mul_f32_e32 v202, v74, v30
	v_mul_f32_e32 v203, v75, v31
	s_waitcnt lgkmcnt(0)
	v_pk_mul_f32 v[12:13], v[12:13], v[228:229]
	v_pk_mul_f32 v[14:15], v[14:15], v[230:231]
	v_pk_mul_f32 v[204:205], v[12:13], v[242:243] op_sel_hi:[1,0]
	v_pk_mul_f32 v[206:207], v[14:15], v[242:243] op_sel_hi:[1,0]
	v_exp_f32_e32 v68, v12
	v_exp_f32_e32 v69, v13
	v_exp_f32_e32 v70, v14
	v_exp_f32_e32 v71, v15
	v_pk_fma_f32 v[208:209], v[204:205], v[244:245], v[238:239] op_sel_hi:[1,0,0]
	v_pk_fma_f32 v[210:211], v[206:207], v[244:245], v[238:239] op_sel_hi:[1,0,0]
	v_pk_fma_f32 v[208:209], v[204:205], v[208:209], v[246:247] op_sel_hi:[1,1,0]
	v_pk_fma_f32 v[210:211], v[206:207], v[210:211], v[246:247] op_sel_hi:[1,1,0]
	v_pk_fma_f32 v[208:209], v[204:205], v[208:209], v[248:249] op_sel_hi:[1,1,0]
	v_pk_fma_f32 v[210:211], v[206:207], v[210:211], v[248:249] op_sel_hi:[1,1,0]
	v_pk_fma_f32 v[208:209], v[204:205], v[208:209], v[240:241] op_sel_hi:[1,1,0]
	v_pk_fma_f32 v[210:211], v[206:207], v[210:211], v[240:241] op_sel_hi:[1,1,0]
	v_pk_mul_f32 v[208:209], v[208:209], v[204:205] neg_lo:[0,1] neg_hi:[0,1]
	v_pk_mul_f32 v[210:211], v[210:211], v[206:207] neg_lo:[0,1] neg_hi:[0,1]
	v_pk_fma_f32 v[212:213], v[68:69], v[68:69], v[240:241] op_sel_hi:[1,1,0] neg_lo:[1,0,0] neg_hi:[1,0,0]
	v_pk_fma_f32 v[214:215], v[70:71], v[70:71], v[240:241] op_sel_hi:[1,1,0] neg_lo:[1,0,0] neg_hi:[1,0,0]
	v_cmp_lt_f32_e64 s[70:71], s29, v204
	v_cmp_lt_f32_e64 s[72:73], s29, v205
	v_cmp_lt_f32_e64 s[74:75], s29, v206
	v_cmp_lt_f32_e64 s[76:77], s29, v207
	v_cndmask_b32_e64 v212, v212, v208, s[70:71]
	v_cndmask_b32_e64 v213, v213, v209, s[72:73]
	v_cndmask_b32_e64 v214, v214, v210, s[74:75]
	v_cndmask_b32_e64 v215, v215, v211, s[76:77]
	v_sqrt_f32_e32 v212, v212
	v_sqrt_f32_e32 v213, v213
	v_sqrt_f32_e32 v214, v214
	v_sqrt_f32_e32 v215, v215
	v_pk_mul_f32 v[72:73], v[200:201], v[212:213]
	v_pk_mul_f32 v[74:75], v[202:203], v[214:215]
	s_nop 1
	v_fmac_f32_dpp v72, v72, v68 row_shr:1 row_mask:0xf bank_mask:0xf
	v_fmac_f32_dpp v73, v73, v69 row_shr:1 row_mask:0xf bank_mask:0xf
	v_fmac_f32_dpp v74, v74, v70 row_shr:1 row_mask:0xf bank_mask:0xf
	v_fmac_f32_dpp v75, v75, v71 row_shr:1 row_mask:0xf bank_mask:0xf
	v_mul_f32_dpp v68, v68, v68 row_shr:1 row_mask:0xf bank_mask:0xf
	v_mul_f32_dpp v69, v69, v69 row_shr:1 row_mask:0xf bank_mask:0xf
	v_mul_f32_dpp v70, v70, v70 row_shr:1 row_mask:0xf bank_mask:0xf
	v_mul_f32_dpp v71, v71, v71 row_shr:1 row_mask:0xf bank_mask:0xf
	v_fmac_f32_dpp v72, v72, v68 row_shr:2 row_mask:0xf bank_mask:0xf
	v_fmac_f32_dpp v73, v73, v69 row_shr:2 row_mask:0xf bank_mask:0xf
	v_fmac_f32_dpp v74, v74, v70 row_shr:2 row_mask:0xf bank_mask:0xf
	v_fmac_f32_dpp v75, v75, v71 row_shr:2 row_mask:0xf bank_mask:0xf
	v_mul_f32_dpp v68, v68, v68 row_shr:2 row_mask:0xf bank_mask:0xf
	v_mul_f32_dpp v69, v69, v69 row_shr:2 row_mask:0xf bank_mask:0xf
	v_mul_f32_dpp v70, v70, v70 row_shr:2 row_mask:0xf bank_mask:0xf
	v_mul_f32_dpp v71, v71, v71 row_shr:2 row_mask:0xf bank_mask:0xf
	v_fmac_f32_dpp v72, v72, v68 row_shr:4 row_mask:0xf bank_mask:0xf
	v_fmac_f32_dpp v73, v73, v69 row_shr:4 row_mask:0xf bank_mask:0xf
	v_fmac_f32_dpp v74, v74, v70 row_shr:4 row_mask:0xf bank_mask:0xf
	v_fmac_f32_dpp v75, v75, v71 row_shr:4 row_mask:0xf bank_mask:0xf
	v_mul_f32_dpp v68, v68, v68 row_shr:4 row_mask:0xf bank_mask:0xf
	v_mul_f32_dpp v69, v69, v69 row_shr:4 row_mask:0xf bank_mask:0xf
	v_mul_f32_dpp v70, v70, v70 row_shr:4 row_mask:0xf bank_mask:0xf
	v_mul_f32_dpp v71, v71, v71 row_shr:4 row_mask:0xf bank_mask:0xf
	v_fmac_f32_dpp v72, v72, v68 row_shr:8 row_mask:0xf bank_mask:0xf
	v_fmac_f32_dpp v73, v73, v69 row_shr:8 row_mask:0xf bank_mask:0xf
	v_fmac_f32_dpp v74, v74, v70 row_shr:8 row_mask:0xf bank_mask:0xf
	v_fmac_f32_dpp v75, v75, v71 row_shr:8 row_mask:0xf bank_mask:0xf
	v_mul_f32_dpp v68, v68, v68 row_shr:8 row_mask:0xf bank_mask:0xf
	v_mul_f32_dpp v69, v69, v69 row_shr:8 row_mask:0xf bank_mask:0xf
	v_mul_f32_dpp v70, v70, v70 row_shr:8 row_mask:0xf bank_mask:0xf
	v_mul_f32_dpp v71, v71, v71 row_shr:8 row_mask:0xf bank_mask:0xf
	v_fmac_f32_dpp v72, v72, v68 row_bcast:15 row_mask:0xa bank_mask:0xf
	v_fmac_f32_dpp v73, v73, v69 row_bcast:15 row_mask:0xa bank_mask:0xf
	v_fmac_f32_dpp v74, v74, v70 row_bcast:15 row_mask:0xa bank_mask:0xf
	v_fmac_f32_dpp v75, v75, v71 row_bcast:15 row_mask:0xa bank_mask:0xf
	v_mul_f32_dpp v68, v68, v68 row_bcast:15 row_mask:0xa bank_mask:0xf
	v_mul_f32_dpp v69, v69, v69 row_bcast:15 row_mask:0xa bank_mask:0xf
	v_mul_f32_dpp v70, v70, v70 row_bcast:15 row_mask:0xa bank_mask:0xf
	v_mul_f32_dpp v71, v71, v71 row_bcast:15 row_mask:0xa bank_mask:0xf
	ds_read_b128 v[216:219], v237 offset:12288
	ds_read_b128 v[220:223], v237 offset:30720
	s_nop 9
	ds_read_b128 v[228:231], v234 offset:39232
	v_exp_f32_e32 v144, v144
	v_exp_f32_e32 v145, v145
	v_exp_f32_e32 v146, v146
	v_exp_f32_e32 v147, v147
	v_exp_f32_e32 v160, v160
	v_exp_f32_e32 v161, v161
	v_exp_f32_e32 v162, v162
	v_exp_f32_e32 v163, v163
	s_waitcnt lgkmcnt(1)
; #define LAS __attribute__((address_space(3)))
; __device__ __forceinline__ void lru_phase(const Ptrs& P, LAS unsigned char* lds, int G, int wave, int lane, int tid) {
;     ...
;         for (int mt = 0; mt < 3; ++mt) {
;             f32x16 gr, gi;
; #pragma unroll
;             for (int i = 0; i < 16; ++i) { gr[i] = 0.f; gi[i] = 0.f; }
;             const LAS bf16x8* wa = (const LAS bf16x8*)(lds + L_WGF) + (size_t)(mt * 6) * 64 + lane;
;             const LAS bf16x8* wb = (const LAS bf16x8*)(lds + L_WGF) + (size_t)((3 + mt) * 6) * 64 + lane;
; #pragma unroll
;             for (int s = 0; s < 5; ++s) { gr = MFMA32(wa[s * 64], xf[s], gr); gi = MFMA32(wb[s * 64], xf[s], gi); }
;             gr = MFMA32(wa[5 * 64], xone, gr); gi = MFMA32(wb[5 * 64], xone, gi);
;             __builtin_amdgcn_sched_barrier(0);
; #pragma unroll
;             for (int i4 = 0; i4 < 4; ++i4) { if (mt == 2 && i4 >= 2) continue;
;                 const int s = 2 * mt + (i4 >> 1), half = i4 & 1, ch0 = 16 * s + 8 * half + 4 * hh;
;                 const f32x4 ls2 = *(const LAS f32x4*)(par + 7 * LB + ch0);
;                 float A4[4], B4[4];
; #pragma unroll
;                 for (int q = 0; q < 4; ++q) { const int i = 4 * i4 + q;
;                     const float rg = rcpf_(1.0f + ex2(gr[i])), ig = rcpf_(1.0f + ex2(gi[i]));
;                     const float la2 = ls2[q] * rg, a = ex2(la2), xx = (2.0f * LN2) * la2;
;                     const float poly = -xx * (1.0f + xx * (0.5f + xx * ((1.0f / 6.0f) + xx * ((1.0f / 24.0f) + xx * (1.0f / 120.0f)))));
;                     const float om = (xx > -0.25f) ? poly : (1.0f - a * a);
;                     A4[q] = a; B4[q] = __builtin_amdgcn_sqrtf(om) * (ig * xc[s][half][q]); }
;                 asm volatile("s_nop 1\n\t"
;                     LRU_DPP4("row_shr:1 row_mask:0xf bank_mask:0xf") LRU_DPP4("row_shr:2 row_mask:0xf bank_mask:0xf") LRU_DPP4("row_shr:4 row_mask:0xf bank_mask:0xf")
;                     LRU_DPP4("row_shr:8 row_mask:0xf bank_mask:0xf") LRU_DPP4("row_bcast:15 row_mask:0xa bank_mask:0xf")
;                     : "+v"(A4[0]), "+v"(A4[1]), "+v"(A4[2]), "+v"(A4[3]), "+v"(B4[0]), "+v"(B4[1]), "+v"(B4[2]), "+v"(B4[3]));
; #pragma unroll
;                 for (int q = 0; q < 4; ++q) { Av[s][half][q] = A4[q]; xc[s][half][q] = B4[q]; }
;                 __builtin_amdgcn_sched_barrier(0); }
	v_mfma_f32_32x32x16_bf16 v[0:15], v[216:219], v[36:39], 0
	ds_read_b128 v[224:227], v237 offset:13312
	v_pk_add_f32 v[144:145], v[144:145], v[240:241] op_sel_hi:[1,0]
	v_pk_add_f32 v[146:147], v[146:147], v[240:241] op_sel_hi:[1,0]
	v_pk_add_f32 v[160:161], v[160:161], v[240:241] op_sel_hi:[1,0]
	v_pk_add_f32 v[162:163], v[162:163], v[240:241] op_sel_hi:[1,0]
	v_rcp_f32_e32 v144, v144
	v_rcp_f32_e32 v145, v145
	v_rcp_f32_e32 v146, v146
	v_rcp_f32_e32 v147, v147
	s_waitcnt lgkmcnt(1)
	v_mfma_f32_32x32x16_bf16 v[16:31], v[220:223], v[36:39], 0
	ds_read_b128 v[216:219], v237 offset:31744
	v_rcp_f32_e32 v160, v160
	v_rcp_f32_e32 v161, v161
	v_rcp_f32_e32 v162, v162
	v_rcp_f32_e32 v163, v163
	v_mul_f32_e32 v200, v81, v160
	v_mul_f32_e32 v201, v82, v161
	v_mul_f32_e32 v202, v86, v162
	v_mul_f32_e32 v203, v87, v163
	s_waitcnt lgkmcnt(1)
	v_mfma_f32_32x32x16_bf16 v[0:15], v[224:227], v[40:43], v[0:15]
	ds_read_b128 v[220:223], v237 offset:14336
	s_waitcnt lgkmcnt(0)
	v_pk_mul_f32 v[144:145], v[144:145], v[228:229]
	v_pk_mul_f32 v[146:147], v[146:147], v[230:231]
	v_pk_mul_f32 v[204:205], v[144:145], v[242:243] op_sel_hi:[1,0]
	v_pk_mul_f32 v[206:207], v[146:147], v[242:243] op_sel_hi:[1,0]
	v_exp_f32_e32 v80, v144
	v_exp_f32_e32 v81, v145
	v_exp_f32_e32 v82, v146
	v_exp_f32_e32 v83, v147
	s_waitcnt lgkmcnt(1)
	v_mfma_f32_32x32x16_bf16 v[16:31], v[216:219], v[40:43], v[16:31]
	ds_read_b128 v[224:227], v237 offset:32768
	v_pk_fma_f32 v[208:209], v[204:205], v[244:245], v[238:239] op_sel_hi:[1,0,0]
	v_pk_fma_f32 v[210:211], v[206:207], v[244:245], v[238:239] op_sel_hi:[1,0,0]
	v_pk_fma_f32 v[208:209], v[204:205], v[208:209], v[246:247] op_sel_hi:[1,1,0]
	v_pk_fma_f32 v[210:211], v[206:207], v[210:211], v[246:247] op_sel_hi:[1,1,0]
	v_pk_fma_f32 v[208:209], v[204:205], v[208:209], v[248:249] op_sel_hi:[1,1,0]
	v_pk_fma_f32 v[210:211], v[206:207], v[210:211], v[248:249] op_sel_hi:[1,1,0]
	v_pk_fma_f32 v[208:209], v[204:205], v[208:209], v[240:241] op_sel_hi:[1,1,0]
	v_pk_fma_f32 v[210:211], v[206:207], v[210:211], v[240:241] op_sel_hi:[1,1,0]
	s_waitcnt lgkmcnt(1)
	v_mfma_f32_32x32x16_bf16 v[0:15], v[220:223], v[76:79], v[0:15]
	ds_read_b128 v[216:219], v237 offset:15360
	v_pk_mul_f32 v[208:209], v[208:209], v[204:205] neg_lo:[0,1] neg_hi:[0,1]
	v_pk_mul_f32 v[210:211], v[210:211], v[206:207] neg_lo:[0,1] neg_hi:[0,1]
	v_pk_fma_f32 v[212:213], v[80:81], v[80:81], v[240:241] op_sel_hi:[1,1,0] neg_lo:[1,0,0] neg_hi:[1,0,0]
	v_pk_fma_f32 v[214:215], v[82:83], v[82:83], v[240:241] op_sel_hi:[1,1,0] neg_lo:[1,0,0] neg_hi:[1,0,0]
	v_cmp_lt_f32_e64 s[70:71], s29, v204
	v_cmp_lt_f32_e64 s[72:73], s29, v205
	v_cmp_lt_f32_e64 s[74:75], s29, v206
	v_cmp_lt_f32_e64 s[76:77], s29, v207
	s_waitcnt lgkmcnt(1)
	v_mfma_f32_32x32x16_bf16 v[16:31], v[224:227], v[76:79], v[16:31]
	ds_read_b128 v[220:223], v237 offset:33792
	v_cndmask_b32_e64 v212, v212, v208, s[70:71]
	v_cndmask_b32_e64 v213, v213, v209, s[72:73]
	v_cndmask_b32_e64 v214, v214, v210, s[74:75]
	v_cndmask_b32_e64 v215, v215, v211, s[76:77]
	v_sqrt_f32_e32 v212, v212
	v_sqrt_f32_e32 v213, v213
	v_sqrt_f32_e32 v214, v214
	v_sqrt_f32_e32 v215, v215
	s_waitcnt lgkmcnt(1)
	v_mfma_f32_32x32x16_bf16 v[0:15], v[216:219], v[112:115], v[0:15]
	ds_read_b128 v[224:227], v237 offset:16384
	v_pk_mul_f32 v[84:85], v[200:201], v[212:213]
	v_pk_mul_f32 v[86:87], v[202:203], v[214:215]
	s_nop 1
	v_fmac_f32_dpp v84, v84, v80 row_shr:1 row_mask:0xf bank_mask:0xf
	v_fmac_f32_dpp v85, v85, v81 row_shr:1 row_mask:0xf bank_mask:0xf
	v_fmac_f32_dpp v86, v86, v82 row_shr:1 row_mask:0xf bank_mask:0xf
	v_fmac_f32_dpp v87, v87, v83 row_shr:1 row_mask:0xf bank_mask:0xf
	v_mul_f32_dpp v80, v80, v80 row_shr:1 row_mask:0xf bank_mask:0xf
	v_mul_f32_dpp v81, v81, v81 row_shr:1 row_mask:0xf bank_mask:0xf
	s_waitcnt lgkmcnt(1)
	v_mfma_f32_32x32x16_bf16 v[16:31], v[220:223], v[112:115], v[16:31]
	ds_read_b128 v[216:219], v237 offset:34816
	v_mul_f32_dpp v82, v82, v82 row_shr:1 row_mask:0xf bank_mask:0xf
	v_mul_f32_dpp v83, v83, v83 row_shr:1 row_mask:0xf bank_mask:0xf
	v_fmac_f32_dpp v84, v84, v80 row_shr:2 row_mask:0xf bank_mask:0xf
	v_fmac_f32_dpp v85, v85, v81 row_shr:2 row_mask:0xf bank_mask:0xf
	v_fmac_f32_dpp v86, v86, v82 row_shr:2 row_mask:0xf bank_mask:0xf
	v_fmac_f32_dpp v87, v87, v83 row_shr:2 row_mask:0xf bank_mask:0xf
	v_mul_f32_dpp v80, v80, v80 row_shr:2 row_mask:0xf bank_mask:0xf
	v_mul_f32_dpp v81, v81, v81 row_shr:2 row_mask:0xf bank_mask:0xf
	s_waitcnt lgkmcnt(1)
	v_mfma_f32_32x32x16_bf16 v[0:15], v[224:227], v[124:127], v[0:15]
	ds_read_b128 v[220:223], v237 offset:17408
	v_mul_f32_dpp v82, v82, v82 row_shr:2 row_mask:0xf bank_mask:0xf
	v_mul_f32_dpp v83, v83, v83 row_shr:2 row_mask:0xf bank_mask:0xf
	v_fmac_f32_dpp v84, v84, v80 row_shr:4 row_mask:0xf bank_mask:0xf
	v_fmac_f32_dpp v85, v85, v81 row_shr:4 row_mask:0xf bank_mask:0xf
	v_fmac_f32_dpp v86, v86, v82 row_shr:4 row_mask:0xf bank_mask:0xf
	v_fmac_f32_dpp v87, v87, v83 row_shr:4 row_mask:0xf bank_mask:0xf
	v_mul_f32_dpp v80, v80, v80 row_shr:4 row_mask:0xf bank_mask:0xf
	v_mul_f32_dpp v81, v81, v81 row_shr:4 row_mask:0xf bank_mask:0xf
	s_waitcnt lgkmcnt(1)
	v_mfma_f32_32x32x16_bf16 v[16:31], v[216:219], v[124:127], v[16:31]
	ds_read_b128 v[224:227], v237 offset:35840
	v_mul_f32_dpp v82, v82, v82 row_shr:4 row_mask:0xf bank_mask:0xf
	v_mul_f32_dpp v83, v83, v83 row_shr:4 row_mask:0xf bank_mask:0xf
	v_fmac_f32_dpp v84, v84, v80 row_shr:8 row_mask:0xf bank_mask:0xf
	v_fmac_f32_dpp v85, v85, v81 row_shr:8 row_mask:0xf bank_mask:0xf
	v_fmac_f32_dpp v86, v86, v82 row_shr:8 row_mask:0xf bank_mask:0xf
	v_fmac_f32_dpp v87, v87, v83 row_shr:8 row_mask:0xf bank_mask:0xf
	v_mul_f32_dpp v80, v80, v80 row_shr:8 row_mask:0xf bank_mask:0xf
	v_mul_f32_dpp v81, v81, v81 row_shr:8 row_mask:0xf bank_mask:0xf
	s_waitcnt lgkmcnt(1)
; #define LAS __attribute__((address_space(3)))
; __device__ __forceinline__ void lru_phase(const Ptrs& P, LAS unsigned char* lds, int G, int wave, int lane, int tid) {
;     ...
;         for (int mt = 0; mt < 3; ++mt) {
;             f32x16 gr, gi;
; #pragma unroll
;             for (int i = 0; i < 16; ++i) { gr[i] = 0.f; gi[i] = 0.f; }
;             const LAS bf16x8* wa = (const LAS bf16x8*)(lds + L_WGF) + (size_t)(mt * 6) * 64 + lane;
;             const LAS bf16x8* wb = (const LAS bf16x8*)(lds + L_WGF) + (size_t)((3 + mt) * 6) * 64 + lane;
; #pragma unroll
;             for (int s = 0; s < 5; ++s) { gr = MFMA32(wa[s * 64], xf[s], gr); gi = MFMA32(wb[s * 64], xf[s], gi); }
;             gr = MFMA32(wa[5 * 64], xone, gr); gi = MFMA32(wb[5 * 64], xone, gi);
;             __builtin_amdgcn_sched_barrier(0);
; #pragma unroll
;             for (int i4 = 0; i4 < 4; ++i4) { if (mt == 2 && i4 >= 2) continue;
;                 const int s = 2 * mt + (i4 >> 1), half = i4 & 1, ch0 = 16 * s + 8 * half + 4 * hh;
;                 const f32x4 ls2 = *(const LAS f32x4*)(par + 7 * LB + ch0);
;                 float A4[4], B4[4];
; #pragma unroll
;                 for (int q = 0; q < 4; ++q) { const int i = 4 * i4 + q;
;                     const float rg = rcpf_(1.0f + ex2(gr[i])), ig = rcpf_(1.0f + ex2(gi[i]));
;                     const float la2 = ls2[q] * rg, a = ex2(la2), xx = (2.0f * LN2) * la2;
;                     const float poly = -xx * (1.0f + xx * (0.5f + xx * ((1.0f / 6.0f) + xx * ((1.0f / 24.0f) + xx * (1.0f / 120.0f)))));
;                     const float om = (xx > -0.25f) ? poly : (1.0f - a * a);
;                     A4[q] = a; B4[q] = __builtin_amdgcn_sqrtf(om) * (ig * xc[s][half][q]); }
;                 asm volatile("s_nop 1\n\t"
;                     LRU_DPP4("row_shr:1 row_mask:0xf bank_mask:0xf") LRU_DPP4("row_shr:2 row_mask:0xf bank_mask:0xf") LRU_DPP4("row_shr:4 row_mask:0xf bank_mask:0xf")
;                     LRU_DPP4("row_shr:8 row_mask:0xf bank_mask:0xf") LRU_DPP4("row_bcast:15 row_mask:0xa bank_mask:0xf")
;                     : "+v"(A4[0]), "+v"(A4[1]), "+v"(A4[2]), "+v"(A4[3]), "+v"(B4[0]), "+v"(B4[1]), "+v"(B4[2]), "+v"(B4[3]));
; #pragma unroll
;                 for (int q = 0; q < 4; ++q) { Av[s][half][q] = A4[q]; xc[s][half][q] = B4[q]; }
;                 __builtin_amdgcn_sched_barrier(0); }
	v_mfma_f32_32x32x16_bf16 v[0:15], v[220:223], v[32:35], v[0:15]
	v_mul_f32_dpp v82, v82, v82 row_shr:8 row_mask:0xf bank_mask:0xf
	v_mul_f32_dpp v83, v83, v83 row_shr:8 row_mask:0xf bank_mask:0xf
	v_fmac_f32_dpp v84, v84, v80 row_bcast:15 row_mask:0xa bank_mask:0xf
	v_fmac_f32_dpp v85, v85, v81 row_bcast:15 row_mask:0xa bank_mask:0xf
	v_fmac_f32_dpp v86, v86, v82 row_bcast:15 row_mask:0xa bank_mask:0xf
	v_fmac_f32_dpp v87, v87, v83 row_bcast:15 row_mask:0xa bank_mask:0xf
	v_mul_f32_dpp v80, v80, v80 row_bcast:15 row_mask:0xa bank_mask:0xf
	v_mul_f32_dpp v81, v81, v81 row_bcast:15 row_mask:0xa bank_mask:0xf
	s_waitcnt lgkmcnt(0)
	v_mfma_f32_32x32x16_bf16 v[16:31], v[224:227], v[32:35], v[16:31]
	v_mul_f32_dpp v82, v82, v82 row_bcast:15 row_mask:0xa bank_mask:0xf
	v_mul_f32_dpp v83, v83, v83 row_bcast:15 row_mask:0xa bank_mask:0xf
	ds_read_b128 v[228:231], v234 offset:39264
	v_exp_f32_e32 v148, v148
	v_exp_f32_e32 v149, v149
	v_exp_f32_e32 v150, v150
	v_exp_f32_e32 v151, v151
	v_exp_f32_e32 v164, v164
	v_exp_f32_e32 v165, v165
	v_exp_f32_e32 v166, v166
	v_exp_f32_e32 v167, v167
	v_pk_add_f32 v[148:149], v[148:149], v[240:241] op_sel_hi:[1,0]
	v_pk_add_f32 v[150:151], v[150:151], v[240:241] op_sel_hi:[1,0]
	v_pk_add_f32 v[164:165], v[164:165], v[240:241] op_sel_hi:[1,0]
	v_pk_add_f32 v[166:167], v[166:167], v[240:241] op_sel_hi:[1,0]
	v_rcp_f32_e32 v148, v148
	v_rcp_f32_e32 v149, v149
	v_rcp_f32_e32 v150, v150
	v_rcp_f32_e32 v151, v151
	v_rcp_f32_e32 v164, v164
	v_rcp_f32_e32 v165, v165
	v_rcp_f32_e32 v166, v166
	v_rcp_f32_e32 v167, v167
	v_mul_f32_e32 v200, v89, v164
	v_mul_f32_e32 v201, v90, v165
	v_mul_f32_e32 v202, v94, v166
	v_mul_f32_e32 v203, v95, v167
	s_waitcnt lgkmcnt(0)
	v_pk_mul_f32 v[148:149], v[148:149], v[228:229]
	v_pk_mul_f32 v[150:151], v[150:151], v[230:231]
	v_pk_mul_f32 v[204:205], v[148:149], v[242:243] op_sel_hi:[1,0]
	v_pk_mul_f32 v[206:207], v[150:151], v[242:243] op_sel_hi:[1,0]
	v_exp_f32_e32 v88, v148
	v_exp_f32_e32 v89, v149
	v_exp_f32_e32 v90, v150
	v_exp_f32_e32 v91, v151
	v_pk_fma_f32 v[208:209], v[204:205], v[244:245], v[238:239] op_sel_hi:[1,0,0]
	v_pk_fma_f32 v[210:211], v[206:207], v[244:245], v[238:239] op_sel_hi:[1,0,0]
	v_pk_fma_f32 v[208:209], v[204:205], v[208:209], v[246:247] op_sel_hi:[1,1,0]
	v_pk_fma_f32 v[210:211], v[206:207], v[210:211], v[246:247] op_sel_hi:[1,1,0]
	v_pk_fma_f32 v[208:209], v[204:205], v[208:209], v[248:249] op_sel_hi:[1,1,0]
	v_pk_fma_f32 v[210:211], v[206:207], v[210:211], v[248:249] op_sel_hi:[1,1,0]
	v_pk_fma_f32 v[208:209], v[204:205], v[208:209], v[240:241] op_sel_hi:[1,1,0]
	v_pk_fma_f32 v[210:211], v[206:207], v[210:211], v[240:241] op_sel_hi:[1,1,0]
	v_pk_mul_f32 v[208:209], v[208:209], v[204:205] neg_lo:[0,1] neg_hi:[0,1]
	v_pk_mul_f32 v[210:211], v[210:211], v[206:207] neg_lo:[0,1] neg_hi:[0,1]
	v_pk_fma_f32 v[212:213], v[88:89], v[88:89], v[240:241] op_sel_hi:[1,1,0] neg_lo:[1,0,0] neg_hi:[1,0,0]
	v_pk_fma_f32 v[214:215], v[90:91], v[90:91], v[240:241] op_sel_hi:[1,1,0] neg_lo:[1,0,0] neg_hi:[1,0,0]
	v_cmp_lt_f32_e64 s[70:71], s29, v204
	v_cmp_lt_f32_e64 s[72:73], s29, v205
	v_cmp_lt_f32_e64 s[74:75], s29, v206
	v_cmp_lt_f32_e64 s[76:77], s29, v207
	v_cndmask_b32_e64 v212, v212, v208, s[70:71]
	v_cndmask_b32_e64 v213, v213, v209, s[72:73]
	v_cndmask_b32_e64 v214, v214, v210, s[74:75]
	v_cndmask_b32_e64 v215, v215, v211, s[76:77]
	v_sqrt_f32_e32 v212, v212
	v_sqrt_f32_e32 v213, v213
	v_sqrt_f32_e32 v214, v214
	v_sqrt_f32_e32 v215, v215
	v_pk_mul_f32 v[92:93], v[200:201], v[212:213]
	v_pk_mul_f32 v[94:95], v[202:203], v[214:215]
	s_nop 1
	v_fmac_f32_dpp v92, v92, v88 row_shr:1 row_mask:0xf bank_mask:0xf
	v_fmac_f32_dpp v93, v93, v89 row_shr:1 row_mask:0xf bank_mask:0xf
	v_fmac_f32_dpp v94, v94, v90 row_shr:1 row_mask:0xf bank_mask:0xf
	v_fmac_f32_dpp v95, v95, v91 row_shr:1 row_mask:0xf bank_mask:0xf
	v_mul_f32_dpp v88, v88, v88 row_shr:1 row_mask:0xf bank_mask:0xf
	v_mul_f32_dpp v89, v89, v89 row_shr:1 row_mask:0xf bank_mask:0xf
	v_mul_f32_dpp v90, v90, v90 row_shr:1 row_mask:0xf bank_mask:0xf
	v_mul_f32_dpp v91, v91, v91 row_shr:1 row_mask:0xf bank_mask:0xf
	v_fmac_f32_dpp v92, v92, v88 row_shr:2 row_mask:0xf bank_mask:0xf
	v_fmac_f32_dpp v93, v93, v89 row_shr:2 row_mask:0xf bank_mask:0xf
	v_fmac_f32_dpp v94, v94, v90 row_shr:2 row_mask:0xf bank_mask:0xf
	v_fmac_f32_dpp v95, v95, v91 row_shr:2 row_mask:0xf bank_mask:0xf
	v_mul_f32_dpp v88, v88, v88 row_shr:2 row_mask:0xf bank_mask:0xf
	v_mul_f32_dpp v89, v89, v89 row_shr:2 row_mask:0xf bank_mask:0xf
	v_mul_f32_dpp v90, v90, v90 row_shr:2 row_mask:0xf bank_mask:0xf
	v_mul_f32_dpp v91, v91, v91 row_shr:2 row_mask:0xf bank_mask:0xf
	v_fmac_f32_dpp v92, v92, v88 row_shr:4 row_mask:0xf bank_mask:0xf
	v_fmac_f32_dpp v93, v93, v89 row_shr:4 row_mask:0xf bank_mask:0xf
	v_fmac_f32_dpp v94, v94, v90 row_shr:4 row_mask:0xf bank_mask:0xf
	v_fmac_f32_dpp v95, v95, v91 row_shr:4 row_mask:0xf bank_mask:0xf
	v_mul_f32_dpp v88, v88, v88 row_shr:4 row_mask:0xf bank_mask:0xf
	v_mul_f32_dpp v89, v89, v89 row_shr:4 row_mask:0xf bank_mask:0xf
	v_mul_f32_dpp v90, v90, v90 row_shr:4 row_mask:0xf bank_mask:0xf
	v_mul_f32_dpp v91, v91, v91 row_shr:4 row_mask:0xf bank_mask:0xf
	v_fmac_f32_dpp v92, v92, v88 row_shr:8 row_mask:0xf bank_mask:0xf
	v_fmac_f32_dpp v93, v93, v89 row_shr:8 row_mask:0xf bank_mask:0xf
	v_fmac_f32_dpp v94, v94, v90 row_shr:8 row_mask:0xf bank_mask:0xf
	v_fmac_f32_dpp v95, v95, v91 row_shr:8 row_mask:0xf bank_mask:0xf
	v_mul_f32_dpp v88, v88, v88 row_shr:8 row_mask:0xf bank_mask:0xf
	v_mul_f32_dpp v89, v89, v89 row_shr:8 row_mask:0xf bank_mask:0xf
	v_mul_f32_dpp v90, v90, v90 row_shr:8 row_mask:0xf bank_mask:0xf
; #define LAS __attribute__((address_space(3)))
; __device__ __forceinline__ void lru_phase(const Ptrs& P, LAS unsigned char* lds, int G, int wave, int lane, int tid) {
;     ...
;         for (int mt = 0; mt < 3; ++mt) {
;             f32x16 gr, gi;
; #pragma unroll
;             for (int i = 0; i < 16; ++i) { gr[i] = 0.f; gi[i] = 0.f; }
;             const LAS bf16x8* wa = (const LAS bf16x8*)(lds + L_WGF) + (size_t)(mt * 6) * 64 + lane;
;             const LAS bf16x8* wb = (const LAS bf16x8*)(lds + L_WGF) + (size_t)((3 + mt) * 6) * 64 + lane;
; #pragma unroll
;             for (int s = 0; s < 5; ++s) { gr = MFMA32(wa[s * 64], xf[s], gr); gi = MFMA32(wb[s * 64], xf[s], gi); }
;             gr = MFMA32(wa[5 * 64], xone, gr); gi = MFMA32(wb[5 * 64], xone, gi);
;             __builtin_amdgcn_sched_barrier(0);
; #pragma unroll
;             for (int i4 = 0; i4 < 4; ++i4) { if (mt == 2 && i4 >= 2) continue;
;                 const int s = 2 * mt + (i4 >> 1), half = i4 & 1, ch0 = 16 * s + 8 * half + 4 * hh;
;                 const f32x4 ls2 = *(const LAS f32x4*)(par + 7 * LB + ch0);
;                 float A4[4], B4[4];
; #pragma unroll
;                 for (int q = 0; q < 4; ++q) { const int i = 4 * i4 + q;
;                     const float rg = rcpf_(1.0f + ex2(gr[i])), ig = rcpf_(1.0f + ex2(gi[i]));
;                     const float la2 = ls2[q] * rg, a = ex2(la2), xx = (2.0f * LN2) * la2;
;                     const float poly = -xx * (1.0f + xx * (0.5f + xx * ((1.0f / 6.0f) + xx * ((1.0f / 24.0f) + xx * (1.0f / 120.0f)))));
;                     const float om = (xx > -0.25f) ? poly : (1.0f - a * a);
;                     A4[q] = a; B4[q] = __builtin_amdgcn_sqrtf(om) * (ig * xc[s][half][q]); }
;                 asm volatile("s_nop 1\n\t"
;                     LRU_DPP4("row_shr:1 row_mask:0xf bank_mask:0xf") LRU_DPP4("row_shr:2 row_mask:0xf bank_mask:0xf") LRU_DPP4("row_shr:4 row_mask:0xf bank_mask:0xf")
;                     LRU_DPP4("row_shr:8 row_mask:0xf bank_mask:0xf") LRU_DPP4("row_bcast:15 row_mask:0xa bank_mask:0xf")
;                     : "+v"(A4[0]), "+v"(A4[1]), "+v"(A4[2]), "+v"(A4[3]), "+v"(B4[0]), "+v"(B4[1]), "+v"(B4[2]), "+v"(B4[3]));
; #pragma unroll
;                 for (int q = 0; q < 4; ++q) { Av[s][half][q] = A4[q]; xc[s][half][q] = B4[q]; }
;                 __builtin_amdgcn_sched_barrier(0); }
	v_mul_f32_dpp v91, v91, v91 row_shr:8 row_mask:0xf bank_mask:0xf
	v_fmac_f32_dpp v92, v92, v88 row_bcast:15 row_mask:0xa bank_mask:0xf
	v_fmac_f32_dpp v93, v93, v89 row_bcast:15 row_mask:0xa bank_mask:0xf
	v_fmac_f32_dpp v94, v94, v90 row_bcast:15 row_mask:0xa bank_mask:0xf
	v_fmac_f32_dpp v95, v95, v91 row_bcast:15 row_mask:0xa bank_mask:0xf
	v_mul_f32_dpp v88, v88, v88 row_bcast:15 row_mask:0xa bank_mask:0xf
	v_mul_f32_dpp v89, v89, v89 row_bcast:15 row_mask:0xa bank_mask:0xf
	v_mul_f32_dpp v90, v90, v90 row_bcast:15 row_mask:0xa bank_mask:0xf
	v_mul_f32_dpp v91, v91, v91 row_bcast:15 row_mask:0xa bank_mask:0xf
	ds_read_b128 v[228:231], v234 offset:39296
	v_exp_f32_e32 v152, v152
	v_exp_f32_e32 v153, v153
	v_exp_f32_e32 v154, v154
	v_exp_f32_e32 v155, v155
	v_exp_f32_e32 v168, v168
	v_exp_f32_e32 v169, v169
	v_exp_f32_e32 v170, v170
	v_exp_f32_e32 v171, v171
	v_pk_add_f32 v[152:153], v[152:153], v[240:241] op_sel_hi:[1,0]
	v_pk_add_f32 v[154:155], v[154:155], v[240:241] op_sel_hi:[1,0]
	v_pk_add_f32 v[168:169], v[168:169], v[240:241] op_sel_hi:[1,0]
	v_pk_add_f32 v[170:171], v[170:171], v[240:241] op_sel_hi:[1,0]
	v_rcp_f32_e32 v152, v152
	v_rcp_f32_e32 v153, v153
	v_rcp_f32_e32 v154, v154
	v_rcp_f32_e32 v155, v155
	v_rcp_f32_e32 v168, v168
	v_rcp_f32_e32 v169, v169
	v_rcp_f32_e32 v170, v170
	v_rcp_f32_e32 v171, v171
	v_mul_f32_e32 v200, v97, v168
	v_mul_f32_e32 v201, v98, v169
	v_mul_f32_e32 v202, v102, v170
	v_mul_f32_e32 v203, v103, v171
	s_waitcnt lgkmcnt(0)
	v_pk_mul_f32 v[152:153], v[152:153], v[228:229]
	v_pk_mul_f32 v[154:155], v[154:155], v[230:231]
	v_pk_mul_f32 v[204:205], v[152:153], v[242:243] op_sel_hi:[1,0]
	v_pk_mul_f32 v[206:207], v[154:155], v[242:243] op_sel_hi:[1,0]
	v_exp_f32_e32 v96, v152
	v_exp_f32_e32 v97, v153
	v_exp_f32_e32 v98, v154
	v_exp_f32_e32 v99, v155
	v_pk_fma_f32 v[208:209], v[204:205], v[244:245], v[238:239] op_sel_hi:[1,0,0]
	v_pk_fma_f32 v[210:211], v[206:207], v[244:245], v[238:239] op_sel_hi:[1,0,0]
	v_pk_fma_f32 v[208:209], v[204:205], v[208:209], v[246:247] op_sel_hi:[1,1,0]
	v_pk_fma_f32 v[210:211], v[206:207], v[210:211], v[246:247] op_sel_hi:[1,1,0]
	v_pk_fma_f32 v[208:209], v[204:205], v[208:209], v[248:249] op_sel_hi:[1,1,0]
	v_pk_fma_f32 v[210:211], v[206:207], v[210:211], v[248:249] op_sel_hi:[1,1,0]
	v_pk_fma_f32 v[208:209], v[204:205], v[208:209], v[240:241] op_sel_hi:[1,1,0]
	v_pk_fma_f32 v[210:211], v[206:207], v[210:211], v[240:241] op_sel_hi:[1,1,0]
	v_pk_mul_f32 v[208:209], v[208:209], v[204:205] neg_lo:[0,1] neg_hi:[0,1]
	v_pk_mul_f32 v[210:211], v[210:211], v[206:207] neg_lo:[0,1] neg_hi:[0,1]
	v_pk_fma_f32 v[212:213], v[96:97], v[96:97], v[240:241] op_sel_hi:[1,1,0] neg_lo:[1,0,0] neg_hi:[1,0,0]
	v_pk_fma_f32 v[214:215], v[98:99], v[98:99], v[240:241] op_sel_hi:[1,1,0] neg_lo:[1,0,0] neg_hi:[1,0,0]
	v_cmp_lt_f32_e64 s[70:71], s29, v204
	v_cmp_lt_f32_e64 s[72:73], s29, v205
	v_cmp_lt_f32_e64 s[74:75], s29, v206
	v_cmp_lt_f32_e64 s[76:77], s29, v207
	v_cndmask_b32_e64 v212, v212, v208, s[70:71]
	v_cndmask_b32_e64 v213, v213, v209, s[72:73]
	v_cndmask_b32_e64 v214, v214, v210, s[74:75]
	v_cndmask_b32_e64 v215, v215, v211, s[76:77]
	v_sqrt_f32_e32 v212, v212
	v_sqrt_f32_e32 v213, v213
	v_sqrt_f32_e32 v214, v214
	v_sqrt_f32_e32 v215, v215
	v_pk_mul_f32 v[100:101], v[200:201], v[212:213]
	v_pk_mul_f32 v[102:103], v[202:203], v[214:215]
	s_nop 1
	v_fmac_f32_dpp v100, v100, v96 row_shr:1 row_mask:0xf bank_mask:0xf
	v_fmac_f32_dpp v101, v101, v97 row_shr:1 row_mask:0xf bank_mask:0xf
	v_fmac_f32_dpp v102, v102, v98 row_shr:1 row_mask:0xf bank_mask:0xf
	v_fmac_f32_dpp v103, v103, v99 row_shr:1 row_mask:0xf bank_mask:0xf
	v_mul_f32_dpp v96, v96, v96 row_shr:1 row_mask:0xf bank_mask:0xf
	v_mul_f32_dpp v97, v97, v97 row_shr:1 row_mask:0xf bank_mask:0xf
	v_mul_f32_dpp v98, v98, v98 row_shr:1 row_mask:0xf bank_mask:0xf
	v_mul_f32_dpp v99, v99, v99 row_shr:1 row_mask:0xf bank_mask:0xf
	v_fmac_f32_dpp v100, v100, v96 row_shr:2 row_mask:0xf bank_mask:0xf
	v_fmac_f32_dpp v101, v101, v97 row_shr:2 row_mask:0xf bank_mask:0xf
	v_fmac_f32_dpp v102, v102, v98 row_shr:2 row_mask:0xf bank_mask:0xf
	v_fmac_f32_dpp v103, v103, v99 row_shr:2 row_mask:0xf bank_mask:0xf
	v_mul_f32_dpp v96, v96, v96 row_shr:2 row_mask:0xf bank_mask:0xf
	v_mul_f32_dpp v97, v97, v97 row_shr:2 row_mask:0xf bank_mask:0xf
	v_mul_f32_dpp v98, v98, v98 row_shr:2 row_mask:0xf bank_mask:0xf
	v_mul_f32_dpp v99, v99, v99 row_shr:2 row_mask:0xf bank_mask:0xf
	v_fmac_f32_dpp v100, v100, v96 row_shr:4 row_mask:0xf bank_mask:0xf
	v_fmac_f32_dpp v101, v101, v97 row_shr:4 row_mask:0xf bank_mask:0xf
	v_fmac_f32_dpp v102, v102, v98 row_shr:4 row_mask:0xf bank_mask:0xf
	v_fmac_f32_dpp v103, v103, v99 row_shr:4 row_mask:0xf bank_mask:0xf
	v_mul_f32_dpp v96, v96, v96 row_shr:4 row_mask:0xf bank_mask:0xf
	v_mul_f32_dpp v97, v97, v97 row_shr:4 row_mask:0xf bank_mask:0xf
	v_mul_f32_dpp v98, v98, v98 row_shr:4 row_mask:0xf bank_mask:0xf
	v_mul_f32_dpp v99, v99, v99 row_shr:4 row_mask:0xf bank_mask:0xf
	v_fmac_f32_dpp v100, v100, v96 row_shr:8 row_mask:0xf bank_mask:0xf
	v_fmac_f32_dpp v101, v101, v97 row_shr:8 row_mask:0xf bank_mask:0xf
	v_fmac_f32_dpp v102, v102, v98 row_shr:8 row_mask:0xf bank_mask:0xf
	v_fmac_f32_dpp v103, v103, v99 row_shr:8 row_mask:0xf bank_mask:0xf
	v_mul_f32_dpp v96, v96, v96 row_shr:8 row_mask:0xf bank_mask:0xf
	v_mul_f32_dpp v97, v97, v97 row_shr:8 row_mask:0xf bank_mask:0xf
	v_mul_f32_dpp v98, v98, v98 row_shr:8 row_mask:0xf bank_mask:0xf
	v_mul_f32_dpp v99, v99, v99 row_shr:8 row_mask:0xf bank_mask:0xf
	v_fmac_f32_dpp v100, v100, v96 row_bcast:15 row_mask:0xa bank_mask:0xf
	v_fmac_f32_dpp v101, v101, v97 row_bcast:15 row_mask:0xa bank_mask:0xf
	v_fmac_f32_dpp v102, v102, v98 row_bcast:15 row_mask:0xa bank_mask:0xf
	v_fmac_f32_dpp v103, v103, v99 row_bcast:15 row_mask:0xa bank_mask:0xf
	v_mul_f32_dpp v96, v96, v96 row_bcast:15 row_mask:0xa bank_mask:0xf
	v_mul_f32_dpp v97, v97, v97 row_bcast:15 row_mask:0xa bank_mask:0xf
	v_mul_f32_dpp v98, v98, v98 row_bcast:15 row_mask:0xa bank_mask:0xf
	v_mul_f32_dpp v99, v99, v99 row_bcast:15 row_mask:0xa bank_mask:0xf
	ds_read_b128 v[228:231], v234 offset:39328
	v_exp_f32_e32 v156, v156
	v_exp_f32_e32 v157, v157
	v_exp_f32_e32 v158, v158
	v_exp_f32_e32 v159, v159
	v_exp_f32_e32 v172, v172
	v_exp_f32_e32 v173, v173
	v_exp_f32_e32 v174, v174
	v_exp_f32_e32 v175, v175
	v_pk_add_f32 v[156:157], v[156:157], v[240:241] op_sel_hi:[1,0]
	v_pk_add_f32 v[158:159], v[158:159], v[240:241] op_sel_hi:[1,0]
	v_pk_add_f32 v[172:173], v[172:173], v[240:241] op_sel_hi:[1,0]
	v_pk_add_f32 v[174:175], v[174:175], v[240:241] op_sel_hi:[1,0]
	v_rcp_f32_e32 v156, v156
	v_rcp_f32_e32 v157, v157
	v_rcp_f32_e32 v158, v158
	v_rcp_f32_e32 v159, v159
	v_rcp_f32_e32 v172, v172
	v_rcp_f32_e32 v173, v173
	v_rcp_f32_e32 v174, v174
	v_rcp_f32_e32 v175, v175
	v_mul_f32_e32 v200, v105, v172
	v_mul_f32_e32 v201, v106, v173
	v_mul_f32_e32 v202, v110, v174
	v_mul_f32_e32 v203, v111, v175
	s_waitcnt lgkmcnt(0)
; #define LAS __attribute__((address_space(3)))
; __device__ __forceinline__ void lru_phase(const Ptrs& P, LAS unsigned char* lds, int G, int wave, int lane, int tid) {
;     ...
;         for (int mt = 0; mt < 3; ++mt) {
;             f32x16 gr, gi;
; #pragma unroll
;             for (int i = 0; i < 16; ++i) { gr[i] = 0.f; gi[i] = 0.f; }
;             const LAS bf16x8* wa = (const LAS bf16x8*)(lds + L_WGF) + (size_t)(mt * 6) * 64 + lane;
;             const LAS bf16x8* wb = (const LAS bf16x8*)(lds + L_WGF) + (size_t)((3 + mt) * 6) * 64 + lane;
; #pragma unroll
;             for (int s = 0; s < 5; ++s) { gr = MFMA32(wa[s * 64], xf[s], gr); gi = MFMA32(wb[s * 64], xf[s], gi); }
;             gr = MFMA32(wa[5 * 64], xone, gr); gi = MFMA32(wb[5 * 64], xone, gi);
;             __builtin_amdgcn_sched_barrier(0);
; #pragma unroll
;             for (int i4 = 0; i4 < 4; ++i4) { if (mt == 2 && i4 >= 2) continue;
;                 const int s = 2 * mt + (i4 >> 1), half = i4 & 1, ch0 = 16 * s + 8 * half + 4 * hh;
;                 const f32x4 ls2 = *(const LAS f32x4*)(par + 7 * LB + ch0);
;                 float A4[4], B4[4];
; #pragma unroll
;                 for (int q = 0; q < 4; ++q) { const int i = 4 * i4 + q;
;                     const float rg = rcpf_(1.0f + ex2(gr[i])), ig = rcpf_(1.0f + ex2(gi[i]));
;                     const float la2 = ls2[q] * rg, a = ex2(la2), xx = (2.0f * LN2) * la2;
;                     const float poly = -xx * (1.0f + xx * (0.5f + xx * ((1.0f / 6.0f) + xx * ((1.0f / 24.0f) + xx * (1.0f / 120.0f)))));
;                     const float om = (xx > -0.25f) ? poly : (1.0f - a * a);
;                     A4[q] = a; B4[q] = __builtin_amdgcn_sqrtf(om) * (ig * xc[s][half][q]); }
;                 asm volatile("s_nop 1\n\t"
;                     LRU_DPP4("row_shr:1 row_mask:0xf bank_mask:0xf") LRU_DPP4("row_shr:2 row_mask:0xf bank_mask:0xf") LRU_DPP4("row_shr:4 row_mask:0xf bank_mask:0xf")
;                     LRU_DPP4("row_shr:8 row_mask:0xf bank_mask:0xf") LRU_DPP4("row_bcast:15 row_mask:0xa bank_mask:0xf")
;                     : "+v"(A4[0]), "+v"(A4[1]), "+v"(A4[2]), "+v"(A4[3]), "+v"(B4[0]), "+v"(B4[1]), "+v"(B4[2]), "+v"(B4[3]));
; #pragma unroll
;                 for (int q = 0; q < 4; ++q) { Av[s][half][q] = A4[q]; xc[s][half][q] = B4[q]; }
;                 __builtin_amdgcn_sched_barrier(0); }
	v_pk_mul_f32 v[156:157], v[156:157], v[228:229]
	v_pk_mul_f32 v[158:159], v[158:159], v[230:231]
	v_pk_mul_f32 v[204:205], v[156:157], v[242:243] op_sel_hi:[1,0]
	v_pk_mul_f32 v[206:207], v[158:159], v[242:243] op_sel_hi:[1,0]
	v_exp_f32_e32 v104, v156
	v_exp_f32_e32 v105, v157
	v_exp_f32_e32 v106, v158
	v_exp_f32_e32 v107, v159
	v_pk_fma_f32 v[208:209], v[204:205], v[244:245], v[238:239] op_sel_hi:[1,0,0]
	v_pk_fma_f32 v[210:211], v[206:207], v[244:245], v[238:239] op_sel_hi:[1,0,0]
	v_pk_fma_f32 v[208:209], v[204:205], v[208:209], v[246:247] op_sel_hi:[1,1,0]
	v_pk_fma_f32 v[210:211], v[206:207], v[210:211], v[246:247] op_sel_hi:[1,1,0]
	v_pk_fma_f32 v[208:209], v[204:205], v[208:209], v[248:249] op_sel_hi:[1,1,0]
	v_pk_fma_f32 v[210:211], v[206:207], v[210:211], v[248:249] op_sel_hi:[1,1,0]
	v_pk_fma_f32 v[208:209], v[204:205], v[208:209], v[240:241] op_sel_hi:[1,1,0]
	v_pk_fma_f32 v[210:211], v[206:207], v[210:211], v[240:241] op_sel_hi:[1,1,0]
	v_pk_mul_f32 v[208:209], v[208:209], v[204:205] neg_lo:[0,1] neg_hi:[0,1]
	v_pk_mul_f32 v[210:211], v[210:211], v[206:207] neg_lo:[0,1] neg_hi:[0,1]
	v_pk_fma_f32 v[212:213], v[104:105], v[104:105], v[240:241] op_sel_hi:[1,1,0] neg_lo:[1,0,0] neg_hi:[1,0,0]
	v_pk_fma_f32 v[214:215], v[106:107], v[106:107], v[240:241] op_sel_hi:[1,1,0] neg_lo:[1,0,0] neg_hi:[1,0,0]
	v_cmp_lt_f32_e64 s[70:71], s29, v204
	v_cmp_lt_f32_e64 s[72:73], s29, v205
	v_cmp_lt_f32_e64 s[74:75], s29, v206
	v_cmp_lt_f32_e64 s[76:77], s29, v207
	v_cndmask_b32_e64 v212, v212, v208, s[70:71]
	v_cndmask_b32_e64 v213, v213, v209, s[72:73]
	v_cndmask_b32_e64 v214, v214, v210, s[74:75]
	v_cndmask_b32_e64 v215, v215, v211, s[76:77]
	v_sqrt_f32_e32 v212, v212
	v_sqrt_f32_e32 v213, v213
	v_sqrt_f32_e32 v214, v214
	v_sqrt_f32_e32 v215, v215
	v_pk_mul_f32 v[108:109], v[200:201], v[212:213]
	v_pk_mul_f32 v[110:111], v[202:203], v[214:215]
	s_nop 1
	v_fmac_f32_dpp v108, v108, v104 row_shr:1 row_mask:0xf bank_mask:0xf
	v_fmac_f32_dpp v109, v109, v105 row_shr:1 row_mask:0xf bank_mask:0xf
	v_fmac_f32_dpp v110, v110, v106 row_shr:1 row_mask:0xf bank_mask:0xf
	v_fmac_f32_dpp v111, v111, v107 row_shr:1 row_mask:0xf bank_mask:0xf
	v_mul_f32_dpp v104, v104, v104 row_shr:1 row_mask:0xf bank_mask:0xf
	v_mul_f32_dpp v105, v105, v105 row_shr:1 row_mask:0xf bank_mask:0xf
	v_mul_f32_dpp v106, v106, v106 row_shr:1 row_mask:0xf bank_mask:0xf
	v_mul_f32_dpp v107, v107, v107 row_shr:1 row_mask:0xf bank_mask:0xf
	v_fmac_f32_dpp v108, v108, v104 row_shr:2 row_mask:0xf bank_mask:0xf
	v_fmac_f32_dpp v109, v109, v105 row_shr:2 row_mask:0xf bank_mask:0xf
	v_fmac_f32_dpp v110, v110, v106 row_shr:2 row_mask:0xf bank_mask:0xf
	v_fmac_f32_dpp v111, v111, v107 row_shr:2 row_mask:0xf bank_mask:0xf
	v_mul_f32_dpp v104, v104, v104 row_shr:2 row_mask:0xf bank_mask:0xf
	v_mul_f32_dpp v105, v105, v105 row_shr:2 row_mask:0xf bank_mask:0xf
	v_mul_f32_dpp v106, v106, v106 row_shr:2 row_mask:0xf bank_mask:0xf
	v_mul_f32_dpp v107, v107, v107 row_shr:2 row_mask:0xf bank_mask:0xf
	v_fmac_f32_dpp v108, v108, v104 row_shr:4 row_mask:0xf bank_mask:0xf
	v_fmac_f32_dpp v109, v109, v105 row_shr:4 row_mask:0xf bank_mask:0xf
	v_fmac_f32_dpp v110, v110, v106 row_shr:4 row_mask:0xf bank_mask:0xf
	v_fmac_f32_dpp v111, v111, v107 row_shr:4 row_mask:0xf bank_mask:0xf
	v_mul_f32_dpp v104, v104, v104 row_shr:4 row_mask:0xf bank_mask:0xf
	v_mul_f32_dpp v105, v105, v105 row_shr:4 row_mask:0xf bank_mask:0xf
	v_mul_f32_dpp v106, v106, v106 row_shr:4 row_mask:0xf bank_mask:0xf
	v_mul_f32_dpp v107, v107, v107 row_shr:4 row_mask:0xf bank_mask:0xf
	v_fmac_f32_dpp v108, v108, v104 row_shr:8 row_mask:0xf bank_mask:0xf
	v_fmac_f32_dpp v109, v109, v105 row_shr:8 row_mask:0xf bank_mask:0xf
	v_fmac_f32_dpp v110, v110, v106 row_shr:8 row_mask:0xf bank_mask:0xf
	v_fmac_f32_dpp v111, v111, v107 row_shr:8 row_mask:0xf bank_mask:0xf
	v_mul_f32_dpp v104, v104, v104 row_shr:8 row_mask:0xf bank_mask:0xf
	v_mul_f32_dpp v105, v105, v105 row_shr:8 row_mask:0xf bank_mask:0xf
	v_mul_f32_dpp v106, v106, v106 row_shr:8 row_mask:0xf bank_mask:0xf
	v_mul_f32_dpp v107, v107, v107 row_shr:8 row_mask:0xf bank_mask:0xf
	v_fmac_f32_dpp v108, v108, v104 row_bcast:15 row_mask:0xa bank_mask:0xf
	v_fmac_f32_dpp v109, v109, v105 row_bcast:15 row_mask:0xa bank_mask:0xf
	v_fmac_f32_dpp v110, v110, v106 row_bcast:15 row_mask:0xa bank_mask:0xf
	v_fmac_f32_dpp v111, v111, v107 row_bcast:15 row_mask:0xa bank_mask:0xf
	v_mul_f32_dpp v104, v104, v104 row_bcast:15 row_mask:0xa bank_mask:0xf
	v_mul_f32_dpp v105, v105, v105 row_bcast:15 row_mask:0xa bank_mask:0xf
	v_mul_f32_dpp v106, v106, v106 row_bcast:15 row_mask:0xa bank_mask:0xf
	v_mul_f32_dpp v107, v107, v107 row_bcast:15 row_mask:0xa bank_mask:0xf
	s_nop 9
	ds_read_b128 v[228:231], v234 offset:39360
	v_exp_f32_e32 v0, v0
	v_exp_f32_e32 v1, v1
	v_exp_f32_e32 v2, v2
	v_exp_f32_e32 v3, v3
	v_exp_f32_e32 v16, v16
	v_exp_f32_e32 v17, v17
	v_exp_f32_e32 v18, v18
	v_exp_f32_e32 v19, v19
	v_pk_add_f32 v[0:1], v[0:1], v[240:241] op_sel_hi:[1,0]
	v_pk_add_f32 v[2:3], v[2:3], v[240:241] op_sel_hi:[1,0]
	v_pk_add_f32 v[16:17], v[16:17], v[240:241] op_sel_hi:[1,0]
	v_pk_add_f32 v[18:19], v[18:19], v[240:241] op_sel_hi:[1,0]
	v_rcp_f32_e32 v0, v0
	v_rcp_f32_e32 v1, v1
	v_rcp_f32_e32 v2, v2
	v_rcp_f32_e32 v3, v3
	v_rcp_f32_e32 v16, v16
	v_rcp_f32_e32 v17, v17
	v_rcp_f32_e32 v18, v18
	v_rcp_f32_e32 v19, v19
	v_mul_f32_e32 v200, v136, v16
	v_mul_f32_e32 v201, v129, v17
	v_mul_f32_e32 v202, v116, v18
	v_mul_f32_e32 v203, v119, v19
	s_waitcnt lgkmcnt(0)
; #define LAS __attribute__((address_space(3)))
; __device__ __forceinline__ void lru_phase(const Ptrs& P, LAS unsigned char* lds, int G, int wave, int lane, int tid) {
;     ...
;         for (int mt = 0; mt < 3; ++mt) {
;             f32x16 gr, gi;
; #pragma unroll
;             for (int i = 0; i < 16; ++i) { gr[i] = 0.f; gi[i] = 0.f; }
;             const LAS bf16x8* wa = (const LAS bf16x8*)(lds + L_WGF) + (size_t)(mt * 6) * 64 + lane;
;             const LAS bf16x8* wb = (const LAS bf16x8*)(lds + L_WGF) + (size_t)((3 + mt) * 6) * 64 + lane;
; #pragma unroll
;             for (int s = 0; s < 5; ++s) { gr = MFMA32(wa[s * 64], xf[s], gr); gi = MFMA32(wb[s * 64], xf[s], gi); }
;             gr = MFMA32(wa[5 * 64], xone, gr); gi = MFMA32(wb[5 * 64], xone, gi);
;             __builtin_amdgcn_sched_barrier(0);
; #pragma unroll
;             for (int i4 = 0; i4 < 4; ++i4) { if (mt == 2 && i4 >= 2) continue;
;                 const int s = 2 * mt + (i4 >> 1), half = i4 & 1, ch0 = 16 * s + 8 * half + 4 * hh;
;                 const f32x4 ls2 = *(const LAS f32x4*)(par + 7 * LB + ch0);
;                 float A4[4], B4[4];
; #pragma unroll
;                 for (int q = 0; q < 4; ++q) { const int i = 4 * i4 + q;
;                     const float rg = rcpf_(1.0f + ex2(gr[i])), ig = rcpf_(1.0f + ex2(gi[i]));
;                     const float la2 = ls2[q] * rg, a = ex2(la2), xx = (2.0f * LN2) * la2;
;                     const float poly = -xx * (1.0f + xx * (0.5f + xx * ((1.0f / 6.0f) + xx * ((1.0f / 24.0f) + xx * (1.0f / 120.0f)))));
;                     const float om = (xx > -0.25f) ? poly : (1.0f - a * a);
;                     A4[q] = a; B4[q] = __builtin_amdgcn_sqrtf(om) * (ig * xc[s][half][q]); }
;                 asm volatile("s_nop 1\n\t"
;                     LRU_DPP4("row_shr:1 row_mask:0xf bank_mask:0xf") LRU_DPP4("row_shr:2 row_mask:0xf bank_mask:0xf") LRU_DPP4("row_shr:4 row_mask:0xf bank_mask:0xf")
;                     LRU_DPP4("row_shr:8 row_mask:0xf bank_mask:0xf") LRU_DPP4("row_bcast:15 row_mask:0xa bank_mask:0xf")
;                     : "+v"(A4[0]), "+v"(A4[1]), "+v"(A4[2]), "+v"(A4[3]), "+v"(B4[0]), "+v"(B4[1]), "+v"(B4[2]), "+v"(B4[3]));
; #pragma unroll
;                 for (int q = 0; q < 4; ++q) { Av[s][half][q] = A4[q]; xc[s][half][q] = B4[q]; }
;                 __builtin_amdgcn_sched_barrier(0); }
	v_pk_mul_f32 v[0:1], v[0:1], v[228:229]
	v_pk_mul_f32 v[2:3], v[2:3], v[230:231]
	v_pk_mul_f32 v[204:205], v[0:1], v[242:243] op_sel_hi:[1,0]
	v_pk_mul_f32 v[206:207], v[2:3], v[242:243] op_sel_hi:[1,0]
	v_exp_f32_e32 v0, v0
	v_exp_f32_e32 v1, v1
	v_exp_f32_e32 v2, v2
	v_exp_f32_e32 v3, v3
	v_pk_fma_f32 v[208:209], v[204:205], v[244:245], v[238:239] op_sel_hi:[1,0,0]
	v_pk_fma_f32 v[210:211], v[206:207], v[244:245], v[238:239] op_sel_hi:[1,0,0]
	v_pk_fma_f32 v[208:209], v[204:205], v[208:209], v[246:247] op_sel_hi:[1,1,0]
	v_pk_fma_f32 v[210:211], v[206:207], v[210:211], v[246:247] op_sel_hi:[1,1,0]
	v_pk_fma_f32 v[208:209], v[204:205], v[208:209], v[248:249] op_sel_hi:[1,1,0]
	v_pk_fma_f32 v[210:211], v[206:207], v[210:211], v[248:249] op_sel_hi:[1,1,0]
	v_pk_fma_f32 v[208:209], v[204:205], v[208:209], v[240:241] op_sel_hi:[1,1,0]
	v_pk_fma_f32 v[210:211], v[206:207], v[210:211], v[240:241] op_sel_hi:[1,1,0]
	v_pk_mul_f32 v[208:209], v[208:209], v[204:205] neg_lo:[0,1] neg_hi:[0,1]
	v_pk_mul_f32 v[210:211], v[210:211], v[206:207] neg_lo:[0,1] neg_hi:[0,1]
	v_pk_fma_f32 v[212:213], v[0:1], v[0:1], v[240:241] op_sel_hi:[1,1,0] neg_lo:[1,0,0] neg_hi:[1,0,0]
	v_pk_fma_f32 v[214:215], v[2:3], v[2:3], v[240:241] op_sel_hi:[1,1,0] neg_lo:[1,0,0] neg_hi:[1,0,0]
	v_cmp_lt_f32_e64 s[70:71], s29, v204
	v_cmp_lt_f32_e64 s[72:73], s29, v205
	v_cmp_lt_f32_e64 s[74:75], s29, v206
	v_cmp_lt_f32_e64 s[76:77], s29, v207
	v_cndmask_b32_e64 v212, v212, v208, s[70:71]
	v_cndmask_b32_e64 v213, v213, v209, s[72:73]
	v_cndmask_b32_e64 v214, v214, v210, s[74:75]
	v_cndmask_b32_e64 v215, v215, v211, s[76:77]
	v_sqrt_f32_e32 v212, v212
	v_sqrt_f32_e32 v213, v213
	v_sqrt_f32_e32 v214, v214
	v_sqrt_f32_e32 v215, v215
	v_pk_mul_f32 v[8:9], v[200:201], v[212:213]
	v_pk_mul_f32 v[10:11], v[202:203], v[214:215]
	s_nop 1
	v_fmac_f32_dpp v8, v8, v0 row_shr:1 row_mask:0xf bank_mask:0xf
	v_fmac_f32_dpp v9, v9, v1 row_shr:1 row_mask:0xf bank_mask:0xf
	v_fmac_f32_dpp v10, v10, v2 row_shr:1 row_mask:0xf bank_mask:0xf
	v_fmac_f32_dpp v11, v11, v3 row_shr:1 row_mask:0xf bank_mask:0xf
	v_mul_f32_dpp v0, v0, v0 row_shr:1 row_mask:0xf bank_mask:0xf
	v_mul_f32_dpp v1, v1, v1 row_shr:1 row_mask:0xf bank_mask:0xf
	v_mul_f32_dpp v2, v2, v2 row_shr:1 row_mask:0xf bank_mask:0xf
	v_mul_f32_dpp v3, v3, v3 row_shr:1 row_mask:0xf bank_mask:0xf
	v_fmac_f32_dpp v8, v8, v0 row_shr:2 row_mask:0xf bank_mask:0xf
	v_fmac_f32_dpp v9, v9, v1 row_shr:2 row_mask:0xf bank_mask:0xf
	v_fmac_f32_dpp v10, v10, v2 row_shr:2 row_mask:0xf bank_mask:0xf
	v_fmac_f32_dpp v11, v11, v3 row_shr:2 row_mask:0xf bank_mask:0xf
	v_mul_f32_dpp v0, v0, v0 row_shr:2 row_mask:0xf bank_mask:0xf
	v_mul_f32_dpp v1, v1, v1 row_shr:2 row_mask:0xf bank_mask:0xf
	v_mul_f32_dpp v2, v2, v2 row_shr:2 row_mask:0xf bank_mask:0xf
	v_mul_f32_dpp v3, v3, v3 row_shr:2 row_mask:0xf bank_mask:0xf
	v_fmac_f32_dpp v8, v8, v0 row_shr:4 row_mask:0xf bank_mask:0xf
	v_fmac_f32_dpp v9, v9, v1 row_shr:4 row_mask:0xf bank_mask:0xf
	v_fmac_f32_dpp v10, v10, v2 row_shr:4 row_mask:0xf bank_mask:0xf
	v_fmac_f32_dpp v11, v11, v3 row_shr:4 row_mask:0xf bank_mask:0xf
	v_mul_f32_dpp v0, v0, v0 row_shr:4 row_mask:0xf bank_mask:0xf
	v_mul_f32_dpp v1, v1, v1 row_shr:4 row_mask:0xf bank_mask:0xf
	v_mul_f32_dpp v2, v2, v2 row_shr:4 row_mask:0xf bank_mask:0xf
	v_mul_f32_dpp v3, v3, v3 row_shr:4 row_mask:0xf bank_mask:0xf
	v_fmac_f32_dpp v8, v8, v0 row_shr:8 row_mask:0xf bank_mask:0xf
	v_fmac_f32_dpp v9, v9, v1 row_shr:8 row_mask:0xf bank_mask:0xf
	v_fmac_f32_dpp v10, v10, v2 row_shr:8 row_mask:0xf bank_mask:0xf
	v_fmac_f32_dpp v11, v11, v3 row_shr:8 row_mask:0xf bank_mask:0xf
	v_mul_f32_dpp v0, v0, v0 row_shr:8 row_mask:0xf bank_mask:0xf
	v_mul_f32_dpp v1, v1, v1 row_shr:8 row_mask:0xf bank_mask:0xf
	v_mul_f32_dpp v2, v2, v2 row_shr:8 row_mask:0xf bank_mask:0xf
	v_mul_f32_dpp v3, v3, v3 row_shr:8 row_mask:0xf bank_mask:0xf
	v_fmac_f32_dpp v8, v8, v0 row_bcast:15 row_mask:0xa bank_mask:0xf
	v_fmac_f32_dpp v9, v9, v1 row_bcast:15 row_mask:0xa bank_mask:0xf
	v_fmac_f32_dpp v10, v10, v2 row_bcast:15 row_mask:0xa bank_mask:0xf
	v_fmac_f32_dpp v11, v11, v3 row_bcast:15 row_mask:0xa bank_mask:0xf
	v_mul_f32_dpp v0, v0, v0 row_bcast:15 row_mask:0xa bank_mask:0xf
	v_mul_f32_dpp v1, v1, v1 row_bcast:15 row_mask:0xa bank_mask:0xf
	v_mul_f32_dpp v2, v2, v2 row_bcast:15 row_mask:0xa bank_mask:0xf
	v_mul_f32_dpp v3, v3, v3 row_bcast:15 row_mask:0xa bank_mask:0xf
	ds_read_b128 v[228:231], v234 offset:39392
	v_exp_f32_e32 v4, v4
	v_exp_f32_e32 v5, v5
	v_exp_f32_e32 v6, v6
	v_exp_f32_e32 v7, v7
	v_exp_f32_e32 v20, v20
	v_exp_f32_e32 v21, v21
	v_exp_f32_e32 v22, v22
	v_exp_f32_e32 v23, v23
	v_pk_add_f32 v[4:5], v[4:5], v[240:241] op_sel_hi:[1,0]
	v_pk_add_f32 v[6:7], v[6:7], v[240:241] op_sel_hi:[1,0]
	v_pk_add_f32 v[20:21], v[20:21], v[240:241] op_sel_hi:[1,0]
	v_pk_add_f32 v[22:23], v[22:23], v[240:241] op_sel_hi:[1,0]
	v_rcp_f32_e32 v4, v4
	v_rcp_f32_e32 v5, v5
	v_rcp_f32_e32 v6, v6
	v_rcp_f32_e32 v7, v7
	v_rcp_f32_e32 v20, v20
	v_rcp_f32_e32 v21, v21
	v_rcp_f32_e32 v22, v22
	v_rcp_f32_e32 v23, v23
	v_mul_f32_e32 v200, v120, v20
	v_mul_f32_e32 v201, v118, v21
	v_mul_f32_e32 v202, v117, v22
	v_mul_f32_e32 v203, v123, v23
	s_waitcnt lgkmcnt(0)
; #define LAS __attribute__((address_space(3)))
; __device__ __forceinline__ void lru_phase(const Ptrs& P, LAS unsigned char* lds, int G, int wave, int lane, int tid) {
;     ...
;         for (int mt = 0; mt < 3; ++mt) {
;             f32x16 gr, gi;
; #pragma unroll
;             for (int i = 0; i < 16; ++i) { gr[i] = 0.f; gi[i] = 0.f; }
;             const LAS bf16x8* wa = (const LAS bf16x8*)(lds + L_WGF) + (size_t)(mt * 6) * 64 + lane;
;             const LAS bf16x8* wb = (const LAS bf16x8*)(lds + L_WGF) + (size_t)((3 + mt) * 6) * 64 + lane;
; #pragma unroll
;             for (int s = 0; s < 5; ++s) { gr = MFMA32(wa[s * 64], xf[s], gr); gi = MFMA32(wb[s * 64], xf[s], gi); }
;             gr = MFMA32(wa[5 * 64], xone, gr); gi = MFMA32(wb[5 * 64], xone, gi);
;             __builtin_amdgcn_sched_barrier(0);
; #pragma unroll
;             for (int i4 = 0; i4 < 4; ++i4) { if (mt == 2 && i4 >= 2) continue;
;                 const int s = 2 * mt + (i4 >> 1), half = i4 & 1, ch0 = 16 * s + 8 * half + 4 * hh;
;                 const f32x4 ls2 = *(const LAS f32x4*)(par + 7 * LB + ch0);
;                 float A4[4], B4[4];
; #pragma unroll
;                 for (int q = 0; q < 4; ++q) { const int i = 4 * i4 + q;
;                     const float rg = rcpf_(1.0f + ex2(gr[i])), ig = rcpf_(1.0f + ex2(gi[i]));
;                     const float la2 = ls2[q] * rg, a = ex2(la2), xx = (2.0f * LN2) * la2;
;                     const float poly = -xx * (1.0f + xx * (0.5f + xx * ((1.0f / 6.0f) + xx * ((1.0f / 24.0f) + xx * (1.0f / 120.0f)))));
;                     const float om = (xx > -0.25f) ? poly : (1.0f - a * a);
;                     A4[q] = a; B4[q] = __builtin_amdgcn_sqrtf(om) * (ig * xc[s][half][q]); }
;                 asm volatile("s_nop 1\n\t"
;                     LRU_DPP4("row_shr:1 row_mask:0xf bank_mask:0xf") LRU_DPP4("row_shr:2 row_mask:0xf bank_mask:0xf") LRU_DPP4("row_shr:4 row_mask:0xf bank_mask:0xf")
;                     LRU_DPP4("row_shr:8 row_mask:0xf bank_mask:0xf") LRU_DPP4("row_bcast:15 row_mask:0xa bank_mask:0xf")
;                     : "+v"(A4[0]), "+v"(A4[1]), "+v"(A4[2]), "+v"(A4[3]), "+v"(B4[0]), "+v"(B4[1]), "+v"(B4[2]), "+v"(B4[3]));
; #pragma unroll
;                 for (int q = 0; q < 4; ++q) { Av[s][half][q] = A4[q]; xc[s][half][q] = B4[q]; }
;                 __builtin_amdgcn_sched_barrier(0); }
	v_pk_mul_f32 v[4:5], v[4:5], v[228:229]
	v_pk_mul_f32 v[6:7], v[6:7], v[230:231]
	v_pk_mul_f32 v[204:205], v[4:5], v[242:243] op_sel_hi:[1,0]
	v_pk_mul_f32 v[206:207], v[6:7], v[242:243] op_sel_hi:[1,0]
	v_exp_f32_e32 v4, v4
	v_exp_f32_e32 v5, v5
	v_exp_f32_e32 v6, v6
	v_exp_f32_e32 v7, v7
	v_pk_fma_f32 v[208:209], v[204:205], v[244:245], v[238:239] op_sel_hi:[1,0,0]
	v_pk_fma_f32 v[210:211], v[206:207], v[244:245], v[238:239] op_sel_hi:[1,0,0]
	v_pk_fma_f32 v[208:209], v[204:205], v[208:209], v[246:247] op_sel_hi:[1,1,0]
	v_pk_fma_f32 v[210:211], v[206:207], v[210:211], v[246:247] op_sel_hi:[1,1,0]
	v_pk_fma_f32 v[208:209], v[204:205], v[208:209], v[248:249] op_sel_hi:[1,1,0]
	v_pk_fma_f32 v[210:211], v[206:207], v[210:211], v[248:249] op_sel_hi:[1,1,0]
	v_pk_fma_f32 v[208:209], v[204:205], v[208:209], v[240:241] op_sel_hi:[1,1,0]
	v_pk_fma_f32 v[210:211], v[206:207], v[210:211], v[240:241] op_sel_hi:[1,1,0]
	v_pk_mul_f32 v[208:209], v[208:209], v[204:205] neg_lo:[0,1] neg_hi:[0,1]
	v_pk_mul_f32 v[210:211], v[210:211], v[206:207] neg_lo:[0,1] neg_hi:[0,1]
	v_pk_fma_f32 v[212:213], v[4:5], v[4:5], v[240:241] op_sel_hi:[1,1,0] neg_lo:[1,0,0] neg_hi:[1,0,0]
	v_pk_fma_f32 v[214:215], v[6:7], v[6:7], v[240:241] op_sel_hi:[1,1,0] neg_lo:[1,0,0] neg_hi:[1,0,0]
	v_cmp_lt_f32_e64 s[70:71], s29, v204
	v_cmp_lt_f32_e64 s[72:73], s29, v205
	v_cmp_lt_f32_e64 s[74:75], s29, v206
	v_cmp_lt_f32_e64 s[76:77], s29, v207
	v_cndmask_b32_e64 v212, v212, v208, s[70:71]
	v_cndmask_b32_e64 v213, v213, v209, s[72:73]
	v_cndmask_b32_e64 v214, v214, v210, s[74:75]
	v_cndmask_b32_e64 v215, v215, v211, s[76:77]
	v_sqrt_f32_e32 v212, v212
	v_sqrt_f32_e32 v213, v213
	v_sqrt_f32_e32 v214, v214
	v_sqrt_f32_e32 v215, v215
	v_pk_mul_f32 v[12:13], v[200:201], v[212:213]
	v_pk_mul_f32 v[14:15], v[202:203], v[214:215]
	s_nop 1
	v_fmac_f32_dpp v12, v12, v4 row_shr:1 row_mask:0xf bank_mask:0xf
	v_fmac_f32_dpp v13, v13, v5 row_shr:1 row_mask:0xf bank_mask:0xf
	v_fmac_f32_dpp v14, v14, v6 row_shr:1 row_mask:0xf bank_mask:0xf
	v_fmac_f32_dpp v15, v15, v7 row_shr:1 row_mask:0xf bank_mask:0xf
	v_mul_f32_dpp v4, v4, v4 row_shr:1 row_mask:0xf bank_mask:0xf
	v_mul_f32_dpp v5, v5, v5 row_shr:1 row_mask:0xf bank_mask:0xf
	v_mul_f32_dpp v6, v6, v6 row_shr:1 row_mask:0xf bank_mask:0xf
	v_mul_f32_dpp v7, v7, v7 row_shr:1 row_mask:0xf bank_mask:0xf
	v_fmac_f32_dpp v12, v12, v4 row_shr:2 row_mask:0xf bank_mask:0xf
	v_fmac_f32_dpp v13, v13, v5 row_shr:2 row_mask:0xf bank_mask:0xf
	v_fmac_f32_dpp v14, v14, v6 row_shr:2 row_mask:0xf bank_mask:0xf
	v_fmac_f32_dpp v15, v15, v7 row_shr:2 row_mask:0xf bank_mask:0xf
	v_mul_f32_dpp v4, v4, v4 row_shr:2 row_mask:0xf bank_mask:0xf
	v_mul_f32_dpp v5, v5, v5 row_shr:2 row_mask:0xf bank_mask:0xf
	v_mul_f32_dpp v6, v6, v6 row_shr:2 row_mask:0xf bank_mask:0xf
	v_mul_f32_dpp v7, v7, v7 row_shr:2 row_mask:0xf bank_mask:0xf
	v_fmac_f32_dpp v12, v12, v4 row_shr:4 row_mask:0xf bank_mask:0xf
	v_fmac_f32_dpp v13, v13, v5 row_shr:4 row_mask:0xf bank_mask:0xf
	v_fmac_f32_dpp v14, v14, v6 row_shr:4 row_mask:0xf bank_mask:0xf
	v_fmac_f32_dpp v15, v15, v7 row_shr:4 row_mask:0xf bank_mask:0xf
	v_mul_f32_dpp v4, v4, v4 row_shr:4 row_mask:0xf bank_mask:0xf
	v_mul_f32_dpp v5, v5, v5 row_shr:4 row_mask:0xf bank_mask:0xf
	v_mul_f32_dpp v6, v6, v6 row_shr:4 row_mask:0xf bank_mask:0xf
	v_mul_f32_dpp v7, v7, v7 row_shr:4 row_mask:0xf bank_mask:0xf
	v_fmac_f32_dpp v12, v12, v4 row_shr:8 row_mask:0xf bank_mask:0xf
	v_fmac_f32_dpp v13, v13, v5 row_shr:8 row_mask:0xf bank_mask:0xf
	v_fmac_f32_dpp v14, v14, v6 row_shr:8 row_mask:0xf bank_mask:0xf
	v_fmac_f32_dpp v15, v15, v7 row_shr:8 row_mask:0xf bank_mask:0xf
	v_mul_f32_dpp v4, v4, v4 row_shr:8 row_mask:0xf bank_mask:0xf
	v_mul_f32_dpp v5, v5, v5 row_shr:8 row_mask:0xf bank_mask:0xf
	v_mul_f32_dpp v6, v6, v6 row_shr:8 row_mask:0xf bank_mask:0xf
	v_mul_f32_dpp v7, v7, v7 row_shr:8 row_mask:0xf bank_mask:0xf
	v_fmac_f32_dpp v12, v12, v4 row_bcast:15 row_mask:0xa bank_mask:0xf
	v_fmac_f32_dpp v13, v13, v5 row_bcast:15 row_mask:0xa bank_mask:0xf
	v_fmac_f32_dpp v14, v14, v6 row_bcast:15 row_mask:0xa bank_mask:0xf
	v_fmac_f32_dpp v15, v15, v7 row_bcast:15 row_mask:0xa bank_mask:0xf
	v_mul_f32_dpp v4, v4, v4 row_bcast:15 row_mask:0xa bank_mask:0xf
	v_mul_f32_dpp v5, v5, v5 row_bcast:15 row_mask:0xa bank_mask:0xf
	v_mul_f32_dpp v6, v6, v6 row_bcast:15 row_mask:0xa bank_mask:0xf
	v_mul_f32_dpp v7, v7, v7 row_bcast:15 row_mask:0xa bank_mask:0xf

; #define LAS __attribute__((address_space(3)))
; __device__ __forceinline__ void lru_phase(const Ptrs& P, LAS unsigned char* lds, int G, int wave, int lane, int tid) {
;     ...
;         { const bf16* gp = U0 + (size_t)M * LW + ((size_t)(((b * 128 + (tloc >> 5)) * 16 + hd) * 10) * 64 + lane) * 4;
; #pragma unroll
;           for (int gq = 0; gq < 10; ++gq) graw_[gq] = *(const v2u*)(gp + gq * 256); }
;         if (r == 31) { LAS float* cp = (LAS float*)(lds + L_COMP) + wave * 160 + 4 * hh;
; #pragma unroll
;             for (int s = 0; s < 5; ++s)
; #pragma unroll
;                 for (int half = 0; half < 2; ++half) { const int ch0 = 16 * s + 8 * half;
;                     *(LAS f32x4*)(cp + ch0) = (f32x4){Av[s][half][0], Av[s][half][1], Av[s][half][2], Av[s][half][3]};
;                     *(LAS f32x4*)(cp + 80 + ch0) = (f32x4){xc[s][half][0], xc[s][half][1], xc[s][half][2], xc[s][half][3]}; } }
	s_lshl_b32 s6, s31, 11
	s_lshr_b32 s7, s34, 1
	s_and_b32 s37, s20, 15
	s_add_i32 s7, s7, s6
	s_or_b32 s6, s7, s37
	s_mul_i32 s6, s6, 10
	s_ashr_i32 s7, s6, 31
	s_lshl_b64 s[6:7], s[6:7], 9
	v_lshl_add_u64 v[16:17], v[130:131], 0, s[6:7]
	global_load_dwordx2 v[200:201], v[16:17], off
	global_load_dwordx2 v[196:197], v[16:17], off offset:512
	global_load_dwordx2 v[194:195], v[16:17], off offset:1024
	global_load_dwordx2 v[192:193], v[16:17], off offset:1536
	global_load_dwordx2 v[190:191], v[16:17], off offset:2048
	global_load_dwordx2 v[188:189], v[16:17], off offset:2560
	global_load_dwordx2 v[182:183], v[16:17], off offset:3072
	global_load_dwordx2 v[180:181], v[16:17], off offset:3584
	v_add_co_u32_e32 v16, vcc, 0x1000, v16
	s_nop 1
	v_addc_co_u32_e32 v17, vcc, 0, v17, vcc
	global_load_dwordx2 v[178:179], v[16:17], off
	global_load_dwordx2 v[176:177], v[16:17], off offset:512
	s_and_saveexec_b64 s[6:7], s[2:3]
	s_cbranch_execz .LBB0_310
	v_add_u32_e32 v16, s27, v233
	ds_write_b128 v16, v[44:47] offset:39424
	ds_write_b128 v16, v[48:51] offset:39744
	ds_write_b128 v16, v[52:55] offset:39456
	ds_write_b128 v16, v[56:59] offset:39776
	ds_write_b128 v16, v[60:63] offset:39488
	ds_write_b128 v16, v[64:67] offset:39808
	ds_write_b128 v16, v[68:71] offset:39520
	ds_write_b128 v16, v[72:75] offset:39840
	ds_write_b128 v16, v[80:83] offset:39552
	ds_write_b128 v16, v[84:87] offset:39872
	ds_write_b128 v16, v[88:91] offset:39584
	ds_write_b128 v16, v[92:95] offset:39904
	ds_write_b128 v16, v[96:99] offset:39616
	ds_write_b128 v16, v[100:103] offset:39936
	ds_write_b128 v16, v[104:107] offset:39648
	ds_write_b128 v16, v[108:111] offset:39968
	ds_write_b128 v16, v[0:3] offset:39680
	ds_write_b128 v16, v[8:11] offset:40000
	ds_write_b128 v16, v[4:7] offset:39712
	ds_write_b128 v16, v[12:15] offset:40032
